# 8-phase GEMM loops: the second s_waitcnt lgkmcnt(0) behind s_barrier / s_setprio 1 deleted where an identical wait already precedes the barrier (no LDS or scalar-memory op in between)
# speedup vs baseline: 1.0077x; 1.0038x over previous
.LBB0_235:
	ds_read_b128 v[128:131], v173
	ds_read_b128 v[132:135], v173 offset:1024
	ds_read_b128 v[152:155], v173 offset:2048
	ds_read_b128 v[178:181], v173 offset:3072
	ds_read_b128 v[184:187], v174
	ds_read_b128 v[188:191], v174 offset:1024
	ds_read_b128 v[192:195], v174 offset:2048
	ds_read_b128 v[196:199], v174 offset:3072
	s_add_u32 s24, s38, 0xfff80080
	s_addc_u32 s25, s39, -1
	s_cmp_eq_u32 s63, 28
	s_cselect_b32 s47, s5, s25
	s_cselect_b32 s46, s6, s24
	s_cselect_b32 s41, s15, s62
	s_cselect_b32 s40, s17, s43
	v_lshl_add_u64 v[232:233], s[38:39], 0, v[144:145]
	s_add_i32 m0, s77, 0xc000
	ds_read_b128 v[200:203], v175
	ds_read_b128 v[204:207], v175 offset:1024
	ds_read_b128 v[208:211], v175 offset:2048
	ds_read_b128 v[212:215], v175 offset:3072
	ds_read_b128 v[216:219], v175 offset:4096
	ds_read_b128 v[220:223], v175 offset:5120
	ds_read_b128 v[224:227], v175 offset:6144
	ds_read_b128 v[228:231], v175 offset:7168
	global_load_lds_dwordx4 v[232:233], off
	v_lshl_add_u64 v[232:233], s[38:39], 0, v[146:147]
	s_add_i32 m0, s77, 0xe000
	s_nop 0
	global_load_lds_dwordx4 v[232:233], off
	s_waitcnt vmcnt(8)
	s_waitcnt lgkmcnt(0)
	s_barrier
	s_setprio 1
	v_mfma_f32_16x16x32_bf16 v[124:127], v[128:131], v[200:203], v[124:127]
	v_mfma_f32_16x16x32_bf16 v[120:123], v[152:155], v[200:203], v[120:123]
	v_mfma_f32_16x16x32_bf16 v[116:119], v[128:131], v[208:211], v[116:119]
	v_mfma_f32_16x16x32_bf16 v[112:115], v[152:155], v[208:211], v[112:115]
	v_mfma_f32_16x16x32_bf16 v[108:111], v[128:131], v[216:219], v[108:111]
	v_mfma_f32_16x16x32_bf16 v[104:107], v[152:155], v[216:219], v[104:107]
	v_mfma_f32_16x16x32_bf16 v[100:103], v[128:131], v[224:227], v[100:103]
	v_mfma_f32_16x16x32_bf16 v[96:99], v[152:155], v[224:227], v[96:99]
	v_mfma_f32_16x16x32_bf16 v[124:127], v[132:135], v[204:207], v[124:127]
	v_mfma_f32_16x16x32_bf16 v[120:123], v[178:181], v[204:207], v[120:123]
	v_mfma_f32_16x16x32_bf16 v[116:119], v[132:135], v[212:215], v[116:119]
	v_mfma_f32_16x16x32_bf16 v[112:115], v[178:181], v[212:215], v[112:115]
	v_mfma_f32_16x16x32_bf16 v[108:111], v[132:135], v[220:223], v[108:111]
	v_mfma_f32_16x16x32_bf16 v[104:107], v[178:181], v[220:223], v[104:107]
	v_mfma_f32_16x16x32_bf16 v[100:103], v[132:135], v[228:231], v[100:103]
	v_mfma_f32_16x16x32_bf16 v[96:99], v[178:181], v[228:231], v[96:99]
	s_setprio 0
	s_setprio 1
	v_mfma_f32_16x16x32_bf16 v[60:63], v[184:187], v[200:203], v[60:63]
	v_mfma_f32_16x16x32_bf16 v[56:59], v[192:195], v[200:203], v[56:59]
	v_mfma_f32_16x16x32_bf16 v[52:55], v[184:187], v[208:211], v[52:55]
	v_mfma_f32_16x16x32_bf16 v[48:51], v[192:195], v[208:211], v[48:51]
	v_mfma_f32_16x16x32_bf16 v[44:47], v[184:187], v[216:219], v[44:47]
	v_mfma_f32_16x16x32_bf16 v[40:43], v[192:195], v[216:219], v[40:43]
	v_mfma_f32_16x16x32_bf16 v[36:39], v[184:187], v[224:227], v[36:39]
	v_mfma_f32_16x16x32_bf16 v[32:35], v[192:195], v[224:227], v[32:35]
	v_mfma_f32_16x16x32_bf16 v[60:63], v[188:191], v[204:207], v[60:63]
	v_mfma_f32_16x16x32_bf16 v[56:59], v[196:199], v[204:207], v[56:59]
	v_mfma_f32_16x16x32_bf16 v[52:55], v[188:191], v[212:215], v[52:55]
	v_mfma_f32_16x16x32_bf16 v[48:51], v[196:199], v[212:215], v[48:51]
	v_mfma_f32_16x16x32_bf16 v[44:47], v[188:191], v[220:223], v[44:47]
	v_mfma_f32_16x16x32_bf16 v[40:43], v[196:199], v[220:223], v[40:43]
	v_mfma_f32_16x16x32_bf16 v[36:39], v[188:191], v[228:231], v[36:39]
	v_mfma_f32_16x16x32_bf16 v[32:35], v[196:199], v[228:231], v[32:35]
	s_setprio 0
	s_barrier
	s_add_i32 s24, s87, s76
	v_lshl_add_u64 v[232:233], s[40:41], 0, v[138:139]
	s_mov_b32 m0, s24
	ds_read_b128 v[200:203], v175 offset:16384
	ds_read_b128 v[204:207], v175 offset:17408
	ds_read_b128 v[208:211], v175 offset:18432
	ds_read_b128 v[212:215], v175 offset:19456
	ds_read_b128 v[216:219], v175 offset:20480
	ds_read_b128 v[220:223], v175 offset:21504
	ds_read_b128 v[224:227], v175 offset:22528
	ds_read_b128 v[228:231], v175 offset:23552
	global_load_lds_dwordx4 v[232:233], off
	s_add_i32 m0, s24, 0x2000
	s_add_u32 s24, s40, 0x80000
	v_lshl_add_u64 v[234:235], s[40:41], 0, v[142:143]
	s_addc_u32 s25, s41, 0
	s_add_i32 s26, s88, s76
	global_load_lds_dwordx4 v[234:235], off
	v_lshl_add_u64 v[236:237], s[24:25], 0, v[138:139]
	s_mov_b32 m0, s26
	v_lshl_add_u64 v[238:239], s[46:47], 0, v[140:141]
	global_load_lds_dwordx4 v[236:237], off
	v_lshl_add_u64 v[236:237], s[24:25], 0, v[142:143]
	s_add_i32 m0, s26, 0x2000
	s_nop 0
	global_load_lds_dwordx4 v[236:237], off
	v_lshl_add_u64 v[236:237], s[46:47], 0, v[136:137]
	s_mov_b32 m0, s77
	s_nop 0
	global_load_lds_dwordx4 v[236:237], off
	s_mov_b32 m0, s78
	s_nop 0
	global_load_lds_dwordx4 v[238:239], off
	s_waitcnt vmcnt(8)
	s_waitcnt lgkmcnt(0)
	s_barrier
	s_setprio 1
	v_mfma_f32_16x16x32_bf16 v[92:95], v[128:131], v[200:203], v[92:95]
	v_mfma_f32_16x16x32_bf16 v[88:91], v[152:155], v[200:203], v[88:91]
	v_mfma_f32_16x16x32_bf16 v[84:87], v[128:131], v[208:211], v[84:87]
	v_mfma_f32_16x16x32_bf16 v[80:83], v[152:155], v[208:211], v[80:83]
	v_mfma_f32_16x16x32_bf16 v[76:79], v[128:131], v[216:219], v[76:79]
	v_mfma_f32_16x16x32_bf16 v[72:75], v[152:155], v[216:219], v[72:75]
	v_mfma_f32_16x16x32_bf16 v[68:71], v[128:131], v[224:227], v[68:71]
	v_mfma_f32_16x16x32_bf16 v[64:67], v[152:155], v[224:227], v[64:67]
	v_mfma_f32_16x16x32_bf16 v[92:95], v[132:135], v[204:207], v[92:95]
	v_mfma_f32_16x16x32_bf16 v[88:91], v[178:181], v[204:207], v[88:91]
	v_mfma_f32_16x16x32_bf16 v[84:87], v[132:135], v[212:215], v[84:87]
	v_mfma_f32_16x16x32_bf16 v[80:83], v[178:181], v[212:215], v[80:83]
	v_mfma_f32_16x16x32_bf16 v[76:79], v[132:135], v[220:223], v[76:79]
	v_mfma_f32_16x16x32_bf16 v[72:75], v[178:181], v[220:223], v[72:75]
	v_mfma_f32_16x16x32_bf16 v[68:71], v[132:135], v[228:231], v[68:71]
	v_mfma_f32_16x16x32_bf16 v[64:67], v[178:181], v[228:231], v[64:67]
	s_setprio 0
	s_setprio 1
	v_mfma_f32_16x16x32_bf16 v[28:31], v[184:187], v[200:203], v[28:31]
	v_mfma_f32_16x16x32_bf16 v[24:27], v[192:195], v[200:203], v[24:27]
	v_mfma_f32_16x16x32_bf16 v[20:23], v[184:187], v[208:211], v[20:23]
	v_mfma_f32_16x16x32_bf16 v[16:19], v[192:195], v[208:211], v[16:19]
	v_mfma_f32_16x16x32_bf16 v[12:15], v[184:187], v[216:219], v[12:15]
	v_mfma_f32_16x16x32_bf16 v[8:11], v[192:195], v[216:219], v[8:11]
	v_mfma_f32_16x16x32_bf16 v[4:7], v[184:187], v[224:227], v[4:7]
	v_mfma_f32_16x16x32_bf16 v[0:3], v[192:195], v[224:227], v[0:3]
	v_mfma_f32_16x16x32_bf16 v[28:31], v[188:191], v[204:207], v[28:31]
	v_mfma_f32_16x16x32_bf16 v[24:27], v[196:199], v[204:207], v[24:27]
	v_mfma_f32_16x16x32_bf16 v[20:23], v[188:191], v[212:215], v[20:23]
	v_mfma_f32_16x16x32_bf16 v[16:19], v[196:199], v[212:215], v[16:19]
	v_mfma_f32_16x16x32_bf16 v[12:15], v[188:191], v[220:223], v[12:15]
	v_mfma_f32_16x16x32_bf16 v[8:11], v[196:199], v[220:223], v[8:11]
	v_mfma_f32_16x16x32_bf16 v[4:7], v[188:191], v[228:231], v[4:7]
	v_mfma_f32_16x16x32_bf16 v[0:3], v[196:199], v[228:231], v[0:3]
	s_setprio 0
	s_barrier
	s_add_i32 s26, 0, 0x18000
	v_add_u32_e32 v177, s26, v166
	s_add_i32 s27, 0, 0x1c000
	ds_read_b128 v[128:131], v177
	ds_read_b128 v[132:135], v177 offset:1024
	ds_read_b128 v[152:155], v177 offset:2048
	ds_read_b128 v[178:181], v177 offset:3072
	v_add_u32_e32 v177, s27, v166
	ds_read_b128 v[184:187], v177
	ds_read_b128 v[188:191], v177 offset:1024
	ds_read_b128 v[192:195], v177 offset:2048
	ds_read_b128 v[196:199], v177 offset:3072
	s_add_u32 s24, s46, 0x80000
	s_addc_u32 s25, s47, 0
	s_mov_b32 m0, s79
	v_lshl_add_u64 v[240:241], s[24:25], 0, v[136:137]
	ds_read_b128 v[200:203], v175 offset:32768
	ds_read_b128 v[204:207], v175 offset:33792
	ds_read_b128 v[208:211], v175 offset:34816
	ds_read_b128 v[212:215], v175 offset:35840
	ds_read_b128 v[216:219], v175 offset:36864
	ds_read_b128 v[220:223], v175 offset:37888
	ds_read_b128 v[224:227], v175 offset:38912
	ds_read_b128 v[228:231], v175 offset:39936
	global_load_lds_dwordx4 v[240:241], off
	v_lshl_add_u64 v[240:241], s[24:25], 0, v[140:141]
	s_mov_b32 m0, s80
	s_nop 0
	global_load_lds_dwordx4 v[240:241], off
	s_waitcnt vmcnt(8)
	s_waitcnt lgkmcnt(0)
	s_barrier
	s_setprio 1
	v_mfma_f32_16x16x32_bf16 v[124:127], v[128:131], v[200:203], v[124:127]
	v_mfma_f32_16x16x32_bf16 v[120:123], v[152:155], v[200:203], v[120:123]
	v_mfma_f32_16x16x32_bf16 v[116:119], v[128:131], v[208:211], v[116:119]
	v_mfma_f32_16x16x32_bf16 v[112:115], v[152:155], v[208:211], v[112:115]
	v_mfma_f32_16x16x32_bf16 v[108:111], v[128:131], v[216:219], v[108:111]
	v_mfma_f32_16x16x32_bf16 v[104:107], v[152:155], v[216:219], v[104:107]
	v_mfma_f32_16x16x32_bf16 v[100:103], v[128:131], v[224:227], v[100:103]
	v_mfma_f32_16x16x32_bf16 v[96:99], v[152:155], v[224:227], v[96:99]
	v_mfma_f32_16x16x32_bf16 v[124:127], v[132:135], v[204:207], v[124:127]
	v_mfma_f32_16x16x32_bf16 v[120:123], v[178:181], v[204:207], v[120:123]
	v_mfma_f32_16x16x32_bf16 v[116:119], v[132:135], v[212:215], v[116:119]
	v_mfma_f32_16x16x32_bf16 v[112:115], v[178:181], v[212:215], v[112:115]
	v_mfma_f32_16x16x32_bf16 v[108:111], v[132:135], v[220:223], v[108:111]
	v_mfma_f32_16x16x32_bf16 v[104:107], v[178:181], v[220:223], v[104:107]
	v_mfma_f32_16x16x32_bf16 v[100:103], v[132:135], v[228:231], v[100:103]
	v_mfma_f32_16x16x32_bf16 v[96:99], v[178:181], v[228:231], v[96:99]
	s_setprio 0
	s_setprio 1
	v_mfma_f32_16x16x32_bf16 v[60:63], v[184:187], v[200:203], v[60:63]
	v_mfma_f32_16x16x32_bf16 v[56:59], v[192:195], v[200:203], v[56:59]
	v_mfma_f32_16x16x32_bf16 v[52:55], v[184:187], v[208:211], v[52:55]
	v_mfma_f32_16x16x32_bf16 v[48:51], v[192:195], v[208:211], v[48:51]
	v_mfma_f32_16x16x32_bf16 v[44:47], v[184:187], v[216:219], v[44:47]
	v_mfma_f32_16x16x32_bf16 v[40:43], v[192:195], v[216:219], v[40:43]
	v_mfma_f32_16x16x32_bf16 v[36:39], v[184:187], v[224:227], v[36:39]
	v_mfma_f32_16x16x32_bf16 v[32:35], v[192:195], v[224:227], v[32:35]
	v_mfma_f32_16x16x32_bf16 v[60:63], v[188:191], v[204:207], v[60:63]
	v_mfma_f32_16x16x32_bf16 v[56:59], v[196:199], v[204:207], v[56:59]
	v_mfma_f32_16x16x32_bf16 v[52:55], v[188:191], v[212:215], v[52:55]
	v_mfma_f32_16x16x32_bf16 v[48:51], v[196:199], v[212:215], v[48:51]
	v_mfma_f32_16x16x32_bf16 v[44:47], v[188:191], v[220:223], v[44:47]
	v_mfma_f32_16x16x32_bf16 v[40:43], v[196:199], v[220:223], v[40:43]
	v_mfma_f32_16x16x32_bf16 v[36:39], v[188:191], v[228:231], v[36:39]
	v_mfma_f32_16x16x32_bf16 v[32:35], v[196:199], v[228:231], v[32:35]
	s_setprio 0
	s_barrier
	s_add_i32 s24, s26, s76
	v_lshl_add_u64 v[232:233], v[232:233], 0, s[10:11]
	s_mov_b32 m0, s24
	ds_read_b128 v[200:203], v175 offset:49152
	ds_read_b128 v[204:207], v175 offset:50176
	ds_read_b128 v[208:211], v175 offset:51200
	ds_read_b128 v[212:215], v175 offset:52224
	ds_read_b128 v[216:219], v175 offset:53248
	ds_read_b128 v[220:223], v175 offset:54272
	ds_read_b128 v[224:227], v175 offset:55296
	ds_read_b128 v[228:231], v175 offset:56320
	global_load_lds_dwordx4 v[232:233], off
	s_add_i32 m0, s24, 0x2000
	s_add_u32 s24, s40, 0x80080
	v_lshl_add_u64 v[232:233], v[234:235], 0, s[10:11]
	s_addc_u32 s25, s41, 0
	s_add_i32 s26, s27, s76
	global_load_lds_dwordx4 v[232:233], off
	v_lshl_add_u64 v[232:233], s[24:25], 0, v[138:139]
	s_mov_b32 m0, s26
	s_nop 0
	global_load_lds_dwordx4 v[232:233], off
	v_lshl_add_u64 v[232:233], s[24:25], 0, v[142:143]
	s_add_i32 m0, s26, 0x2000
	s_nop 0
	global_load_lds_dwordx4 v[232:233], off
	v_lshl_add_u64 v[232:233], v[236:237], 0, s[10:11]
	s_mov_b32 m0, s81
	s_nop 0
	global_load_lds_dwordx4 v[232:233], off
	v_lshl_add_u64 v[232:233], v[238:239], 0, s[10:11]
	s_mov_b32 m0, s82
	s_nop 0
	global_load_lds_dwordx4 v[232:233], off
	s_waitcnt vmcnt(8)
	s_waitcnt lgkmcnt(0)
	s_barrier
	s_setprio 1
	v_mfma_f32_16x16x32_bf16 v[92:95], v[128:131], v[200:203], v[92:95]
	v_mfma_f32_16x16x32_bf16 v[88:91], v[152:155], v[200:203], v[88:91]
	v_mfma_f32_16x16x32_bf16 v[84:87], v[128:131], v[208:211], v[84:87]
	v_mfma_f32_16x16x32_bf16 v[80:83], v[152:155], v[208:211], v[80:83]
	v_mfma_f32_16x16x32_bf16 v[76:79], v[128:131], v[216:219], v[76:79]
	v_mfma_f32_16x16x32_bf16 v[72:75], v[152:155], v[216:219], v[72:75]
	v_mfma_f32_16x16x32_bf16 v[68:71], v[128:131], v[224:227], v[68:71]
	v_mfma_f32_16x16x32_bf16 v[64:67], v[152:155], v[224:227], v[64:67]
	v_mfma_f32_16x16x32_bf16 v[92:95], v[132:135], v[204:207], v[92:95]
	v_mfma_f32_16x16x32_bf16 v[88:91], v[178:181], v[204:207], v[88:91]
	v_mfma_f32_16x16x32_bf16 v[84:87], v[132:135], v[212:215], v[84:87]
	v_mfma_f32_16x16x32_bf16 v[80:83], v[178:181], v[212:215], v[80:83]
	v_mfma_f32_16x16x32_bf16 v[76:79], v[132:135], v[220:223], v[76:79]
	v_mfma_f32_16x16x32_bf16 v[72:75], v[178:181], v[220:223], v[72:75]
	v_mfma_f32_16x16x32_bf16 v[68:71], v[132:135], v[228:231], v[68:71]
	v_mfma_f32_16x16x32_bf16 v[64:67], v[178:181], v[228:231], v[64:67]
	s_setprio 0
	s_setprio 1
	v_mfma_f32_16x16x32_bf16 v[28:31], v[184:187], v[200:203], v[28:31]
	v_mfma_f32_16x16x32_bf16 v[24:27], v[192:195], v[200:203], v[24:27]
	v_mfma_f32_16x16x32_bf16 v[20:23], v[184:187], v[208:211], v[20:23]
	v_mfma_f32_16x16x32_bf16 v[16:19], v[192:195], v[208:211], v[16:19]
	v_mfma_f32_16x16x32_bf16 v[12:15], v[184:187], v[216:219], v[12:15]
	v_mfma_f32_16x16x32_bf16 v[8:11], v[192:195], v[216:219], v[8:11]
	v_mfma_f32_16x16x32_bf16 v[4:7], v[184:187], v[224:227], v[4:7]
	v_mfma_f32_16x16x32_bf16 v[0:3], v[192:195], v[224:227], v[0:3]
	v_mfma_f32_16x16x32_bf16 v[28:31], v[188:191], v[204:207], v[28:31]
	v_mfma_f32_16x16x32_bf16 v[24:27], v[196:199], v[204:207], v[24:27]
	v_mfma_f32_16x16x32_bf16 v[20:23], v[188:191], v[212:215], v[20:23]
	v_mfma_f32_16x16x32_bf16 v[16:19], v[196:199], v[212:215], v[16:19]
	v_mfma_f32_16x16x32_bf16 v[12:15], v[188:191], v[220:223], v[12:15]
	v_mfma_f32_16x16x32_bf16 v[8:11], v[196:199], v[220:223], v[8:11]
	v_mfma_f32_16x16x32_bf16 v[4:7], v[188:191], v[228:231], v[4:7]
	v_mfma_f32_16x16x32_bf16 v[0:3], v[196:199], v[228:231], v[0:3]
	s_setprio 0
	s_barrier
	s_add_i32 s63, s63, 2
	s_add_u32 s38, s38, 0x100
	s_addc_u32 s39, s39, 0
	s_add_u32 s43, s43, 0x100
	s_addc_u32 s62, s62, 0
	s_cmp_gt_u32 s63, 29
	s_cbranch_scc0 .LBB0_235
	s_and_b64 vcc, exec, s[12:13]
	s_cbranch_vccz .LBB0_238
	s_barrier

.LBB0_349:
	ds_read_b128 v[16:19], v186
	ds_read_b128 v[20:23], v186 offset:1024
	ds_read_b128 v[24:27], v186 offset:2048
	ds_read_b128 v[28:31], v186 offset:3072
	ds_read_b128 v[0:3], v187
	ds_read_b128 v[4:7], v187 offset:1024
	ds_read_b128 v[8:11], v187 offset:2048
	ds_read_b128 v[12:15], v187 offset:3072
	s_add_u32 s24, s62, 0xfffc0080
	s_addc_u32 s25, s63, -1
	s_cmp_eq_u32 s71, 12
	s_cselect_b32 s69, s1, s25
	s_cselect_b32 s68, s8, s24
	s_cselect_b32 s67, s23, s70
	s_cselect_b32 s66, s39, s65
	v_lshl_add_u64 v[214:215], s[62:63], 0, v[170:171]
	s_add_i32 m0, s81, 0xc000
	ds_read_b128 v[174:177], v188
	ds_read_b128 v[178:181], v188 offset:1024
	ds_read_b128 v[190:193], v188 offset:2048
	ds_read_b128 v[194:197], v188 offset:3072
	ds_read_b128 v[198:201], v188 offset:4096
	ds_read_b128 v[202:205], v188 offset:5120
	ds_read_b128 v[206:209], v188 offset:6144
	ds_read_b128 v[210:213], v188 offset:7168
	global_load_lds_dwordx4 v[214:215], off
	v_lshl_add_u64 v[214:215], s[62:63], 0, v[172:173]
	s_add_i32 m0, s81, 0xe000
	s_nop 0
	global_load_lds_dwordx4 v[214:215], off
	s_waitcnt vmcnt(8)
	s_waitcnt lgkmcnt(0)
	s_barrier
	s_setprio 1
	v_mfma_scale_f32_16x16x128_f8f6f4 v[156:159], v[16:23], v[174:181], v[156:159], v189, v189 op_sel_hi:[0,0,0]
	v_mfma_scale_f32_16x16x128_f8f6f4 v[152:155], v[24:31], v[174:181], v[152:155], v189, v189 op_sel_hi:[0,0,0]
	v_mfma_scale_f32_16x16x128_f8f6f4 v[148:151], v[16:23], v[190:197], v[148:151], v189, v189 op_sel_hi:[0,0,0]
	v_mfma_scale_f32_16x16x128_f8f6f4 v[144:147], v[24:31], v[190:197], v[144:147], v189, v189 op_sel_hi:[0,0,0]
	v_mfma_scale_f32_16x16x128_f8f6f4 v[140:143], v[16:23], v[198:205], v[140:143], v189, v189 op_sel_hi:[0,0,0]
	v_mfma_scale_f32_16x16x128_f8f6f4 v[136:139], v[24:31], v[198:205], v[136:139], v189, v189 op_sel_hi:[0,0,0]
	v_mfma_scale_f32_16x16x128_f8f6f4 v[132:135], v[16:23], v[206:213], v[132:135], v189, v189 op_sel_hi:[0,0,0]
	v_mfma_scale_f32_16x16x128_f8f6f4 v[128:131], v[24:31], v[206:213], v[128:131], v189, v189 op_sel_hi:[0,0,0]
	s_setprio 0
	s_setprio 1
	v_mfma_scale_f32_16x16x128_f8f6f4 v[92:95], v[0:7], v[174:181], v[92:95], v189, v189 op_sel_hi:[0,0,0]
	v_mfma_scale_f32_16x16x128_f8f6f4 v[88:91], v[8:15], v[174:181], v[88:91], v189, v189 op_sel_hi:[0,0,0]
	v_mfma_scale_f32_16x16x128_f8f6f4 v[84:87], v[0:7], v[190:197], v[84:87], v189, v189 op_sel_hi:[0,0,0]
	v_mfma_scale_f32_16x16x128_f8f6f4 v[80:83], v[8:15], v[190:197], v[80:83], v189, v189 op_sel_hi:[0,0,0]
	v_mfma_scale_f32_16x16x128_f8f6f4 v[76:79], v[0:7], v[198:205], v[76:79], v189, v189 op_sel_hi:[0,0,0]
	v_mfma_scale_f32_16x16x128_f8f6f4 v[72:75], v[8:15], v[198:205], v[72:75], v189, v189 op_sel_hi:[0,0,0]
	v_mfma_scale_f32_16x16x128_f8f6f4 v[68:71], v[0:7], v[206:213], v[68:71], v189, v189 op_sel_hi:[0,0,0]
	v_mfma_scale_f32_16x16x128_f8f6f4 v[64:67], v[8:15], v[206:213], v[64:67], v189, v189 op_sel_hi:[0,0,0]
	s_setprio 0
	s_barrier
	s_add_i32 s24, s90, s80
	v_lshl_add_u64 v[174:175], s[66:67], 0, v[162:163]
	s_mov_b32 m0, s24
	ds_read_b128 v[190:193], v188 offset:16384
	ds_read_b128 v[194:197], v188 offset:17408
	ds_read_b128 v[198:201], v188 offset:18432
	ds_read_b128 v[202:205], v188 offset:19456
	ds_read_b128 v[206:209], v188 offset:20480
	ds_read_b128 v[210:213], v188 offset:21504
	ds_read_b128 v[214:217], v188 offset:22528
	ds_read_b128 v[218:221], v188 offset:23552
	global_load_lds_dwordx4 v[174:175], off
	s_add_i32 m0, s24, 0x2000
	s_add_u32 s24, s66, 0x40000
	v_lshl_add_u64 v[176:177], s[66:67], 0, v[166:167]
	s_addc_u32 s25, s67, 0
	s_add_i32 s26, s91, s80
	global_load_lds_dwordx4 v[176:177], off
	v_lshl_add_u64 v[178:179], s[24:25], 0, v[162:163]
	s_mov_b32 m0, s26
	v_lshl_add_u64 v[180:181], s[68:69], 0, v[164:165]
	global_load_lds_dwordx4 v[178:179], off
	v_lshl_add_u64 v[178:179], s[24:25], 0, v[166:167]
	s_add_i32 m0, s26, 0x2000
	s_nop 0
	global_load_lds_dwordx4 v[178:179], off
	v_lshl_add_u64 v[178:179], s[68:69], 0, v[160:161]
	s_mov_b32 m0, s81
	s_nop 0
	global_load_lds_dwordx4 v[178:179], off
	s_mov_b32 m0, s82
	s_nop 0
	global_load_lds_dwordx4 v[180:181], off
	s_waitcnt vmcnt(8)
	s_waitcnt lgkmcnt(0)
	s_barrier
	s_setprio 1
	v_mfma_scale_f32_16x16x128_f8f6f4 v[124:127], v[16:23], v[190:197], v[124:127], v189, v189 op_sel_hi:[0,0,0]
	v_mfma_scale_f32_16x16x128_f8f6f4 v[120:123], v[24:31], v[190:197], v[120:123], v189, v189 op_sel_hi:[0,0,0]
	v_mfma_scale_f32_16x16x128_f8f6f4 v[116:119], v[16:23], v[198:205], v[116:119], v189, v189 op_sel_hi:[0,0,0]
	v_mfma_scale_f32_16x16x128_f8f6f4 v[112:115], v[24:31], v[198:205], v[112:115], v189, v189 op_sel_hi:[0,0,0]
	v_mfma_scale_f32_16x16x128_f8f6f4 v[108:111], v[16:23], v[206:213], v[108:111], v189, v189 op_sel_hi:[0,0,0]
	v_mfma_scale_f32_16x16x128_f8f6f4 v[104:107], v[24:31], v[206:213], v[104:107], v189, v189 op_sel_hi:[0,0,0]
	v_mfma_scale_f32_16x16x128_f8f6f4 v[100:103], v[16:23], v[214:221], v[100:103], v189, v189 op_sel_hi:[0,0,0]
	v_mfma_scale_f32_16x16x128_f8f6f4 v[96:99], v[24:31], v[214:221], v[96:99], v189, v189 op_sel_hi:[0,0,0]
	s_setprio 0
	s_setprio 1
	v_mfma_scale_f32_16x16x128_f8f6f4 v[60:63], v[0:7], v[190:197], v[60:63], v189, v189 op_sel_hi:[0,0,0]
	v_mfma_scale_f32_16x16x128_f8f6f4 v[56:59], v[8:15], v[190:197], v[56:59], v189, v189 op_sel_hi:[0,0,0]
	v_mfma_scale_f32_16x16x128_f8f6f4 v[52:55], v[0:7], v[198:205], v[52:55], v189, v189 op_sel_hi:[0,0,0]
	v_mfma_scale_f32_16x16x128_f8f6f4 v[48:51], v[8:15], v[198:205], v[48:51], v189, v189 op_sel_hi:[0,0,0]
	v_mfma_scale_f32_16x16x128_f8f6f4 v[44:47], v[0:7], v[206:213], v[44:47], v189, v189 op_sel_hi:[0,0,0]
	v_mfma_scale_f32_16x16x128_f8f6f4 v[40:43], v[8:15], v[206:213], v[40:43], v189, v189 op_sel_hi:[0,0,0]
	v_mfma_scale_f32_16x16x128_f8f6f4 v[36:39], v[0:7], v[214:221], v[36:39], v189, v189 op_sel_hi:[0,0,0]
	v_mfma_scale_f32_16x16x128_f8f6f4 v[32:35], v[8:15], v[214:221], v[32:35], v189, v189 op_sel_hi:[0,0,0]
	s_setprio 0
	s_barrier
	s_add_i32 s26, 0, 0x18000
	s_add_i32 s27, 0, 0x1c000
	v_add_u32_e32 v12, s26, v184
	v_add_u32_e32 v28, s27, v184
	ds_read_b128 v[0:3], v12
	ds_read_b128 v[4:7], v12 offset:1024
	ds_read_b128 v[8:11], v12 offset:2048
	ds_read_b128 v[12:15], v12 offset:3072
	ds_read_b128 v[16:19], v28
	ds_read_b128 v[20:23], v28 offset:1024
	ds_read_b128 v[24:27], v28 offset:2048
	ds_read_b128 v[28:31], v28 offset:3072
	s_add_u32 s24, s68, 0x40000
	s_addc_u32 s25, s69, 0
	s_mov_b32 m0, s83
	v_lshl_add_u64 v[222:223], s[24:25], 0, v[160:161]
	ds_read_b128 v[190:193], v188 offset:32768
	ds_read_b128 v[194:197], v188 offset:33792
	ds_read_b128 v[198:201], v188 offset:34816
	ds_read_b128 v[202:205], v188 offset:35840
	ds_read_b128 v[206:209], v188 offset:36864
	ds_read_b128 v[210:213], v188 offset:37888
	ds_read_b128 v[214:217], v188 offset:38912
	ds_read_b128 v[218:221], v188 offset:39936
	global_load_lds_dwordx4 v[222:223], off
	v_lshl_add_u64 v[222:223], s[24:25], 0, v[164:165]
	s_mov_b32 m0, s84
	s_nop 0
	global_load_lds_dwordx4 v[222:223], off
	s_waitcnt vmcnt(8)
	s_waitcnt lgkmcnt(0)
	s_barrier
	s_setprio 1
	v_mfma_scale_f32_16x16x128_f8f6f4 v[156:159], v[0:7], v[190:197], v[156:159], v189, v189 op_sel_hi:[0,0,0]
	v_mfma_scale_f32_16x16x128_f8f6f4 v[152:155], v[8:15], v[190:197], v[152:155], v189, v189 op_sel_hi:[0,0,0]
	v_mfma_scale_f32_16x16x128_f8f6f4 v[148:151], v[0:7], v[198:205], v[148:151], v189, v189 op_sel_hi:[0,0,0]
	v_mfma_scale_f32_16x16x128_f8f6f4 v[144:147], v[8:15], v[198:205], v[144:147], v189, v189 op_sel_hi:[0,0,0]
	v_mfma_scale_f32_16x16x128_f8f6f4 v[140:143], v[0:7], v[206:213], v[140:143], v189, v189 op_sel_hi:[0,0,0]
	v_mfma_scale_f32_16x16x128_f8f6f4 v[136:139], v[8:15], v[206:213], v[136:139], v189, v189 op_sel_hi:[0,0,0]
	v_mfma_scale_f32_16x16x128_f8f6f4 v[132:135], v[0:7], v[214:221], v[132:135], v189, v189 op_sel_hi:[0,0,0]
	v_mfma_scale_f32_16x16x128_f8f6f4 v[128:131], v[8:15], v[214:221], v[128:131], v189, v189 op_sel_hi:[0,0,0]
	s_setprio 0
	s_setprio 1
	v_mfma_scale_f32_16x16x128_f8f6f4 v[92:95], v[16:23], v[190:197], v[92:95], v189, v189 op_sel_hi:[0,0,0]
	v_mfma_scale_f32_16x16x128_f8f6f4 v[88:91], v[24:31], v[190:197], v[88:91], v189, v189 op_sel_hi:[0,0,0]
	v_mfma_scale_f32_16x16x128_f8f6f4 v[84:87], v[16:23], v[198:205], v[84:87], v189, v189 op_sel_hi:[0,0,0]
	v_mfma_scale_f32_16x16x128_f8f6f4 v[80:83], v[24:31], v[198:205], v[80:83], v189, v189 op_sel_hi:[0,0,0]
	v_mfma_scale_f32_16x16x128_f8f6f4 v[76:79], v[16:23], v[206:213], v[76:79], v189, v189 op_sel_hi:[0,0,0]
	v_mfma_scale_f32_16x16x128_f8f6f4 v[72:75], v[24:31], v[206:213], v[72:75], v189, v189 op_sel_hi:[0,0,0]
	v_mfma_scale_f32_16x16x128_f8f6f4 v[68:71], v[16:23], v[214:221], v[68:71], v189, v189 op_sel_hi:[0,0,0]
	v_mfma_scale_f32_16x16x128_f8f6f4 v[64:67], v[24:31], v[214:221], v[64:67], v189, v189 op_sel_hi:[0,0,0]
	s_setprio 0
	s_barrier
	s_add_i32 s24, s26, s80
	v_lshl_add_u64 v[174:175], v[174:175], 0, s[12:13]
	s_mov_b32 m0, s24
	ds_read_b128 v[190:193], v188 offset:49152
	ds_read_b128 v[194:197], v188 offset:50176
	ds_read_b128 v[198:201], v188 offset:51200
	ds_read_b128 v[202:205], v188 offset:52224
	ds_read_b128 v[206:209], v188 offset:53248
	ds_read_b128 v[210:213], v188 offset:54272
	ds_read_b128 v[214:217], v188 offset:55296
	ds_read_b128 v[218:221], v188 offset:56320
	global_load_lds_dwordx4 v[174:175], off
	s_add_i32 m0, s24, 0x2000
	s_add_u32 s24, s66, 0x40080
	v_lshl_add_u64 v[174:175], v[176:177], 0, s[12:13]
	s_addc_u32 s25, s67, 0
	s_add_i32 s26, s27, s80
	global_load_lds_dwordx4 v[174:175], off
	v_lshl_add_u64 v[174:175], s[24:25], 0, v[162:163]
	s_mov_b32 m0, s26
	s_nop 0
	global_load_lds_dwordx4 v[174:175], off
	v_lshl_add_u64 v[174:175], s[24:25], 0, v[166:167]
	s_add_i32 m0, s26, 0x2000
	s_nop 0
	global_load_lds_dwordx4 v[174:175], off
	v_lshl_add_u64 v[174:175], v[178:179], 0, s[12:13]
	s_mov_b32 m0, s86
	s_nop 0
	global_load_lds_dwordx4 v[174:175], off
	v_lshl_add_u64 v[174:175], v[180:181], 0, s[12:13]
	s_mov_b32 m0, s87
	s_nop 0
	global_load_lds_dwordx4 v[174:175], off
	s_waitcnt vmcnt(8)
	s_waitcnt lgkmcnt(0)
	s_barrier
	s_setprio 1
	v_mfma_scale_f32_16x16x128_f8f6f4 v[124:127], v[0:7], v[190:197], v[124:127], v189, v189 op_sel_hi:[0,0,0]
	v_mfma_scale_f32_16x16x128_f8f6f4 v[120:123], v[8:15], v[190:197], v[120:123], v189, v189 op_sel_hi:[0,0,0]
	v_mfma_scale_f32_16x16x128_f8f6f4 v[116:119], v[0:7], v[198:205], v[116:119], v189, v189 op_sel_hi:[0,0,0]
	v_mfma_scale_f32_16x16x128_f8f6f4 v[112:115], v[8:15], v[198:205], v[112:115], v189, v189 op_sel_hi:[0,0,0]
	v_mfma_scale_f32_16x16x128_f8f6f4 v[108:111], v[0:7], v[206:213], v[108:111], v189, v189 op_sel_hi:[0,0,0]
	v_mfma_scale_f32_16x16x128_f8f6f4 v[104:107], v[8:15], v[206:213], v[104:107], v189, v189 op_sel_hi:[0,0,0]
	v_mfma_scale_f32_16x16x128_f8f6f4 v[100:103], v[0:7], v[214:221], v[100:103], v189, v189 op_sel_hi:[0,0,0]
	v_mfma_scale_f32_16x16x128_f8f6f4 v[96:99], v[8:15], v[214:221], v[96:99], v189, v189 op_sel_hi:[0,0,0]
	s_setprio 0
	s_setprio 1
	v_mfma_scale_f32_16x16x128_f8f6f4 v[60:63], v[16:23], v[190:197], v[60:63], v189, v189 op_sel_hi:[0,0,0]
	v_mfma_scale_f32_16x16x128_f8f6f4 v[56:59], v[24:31], v[190:197], v[56:59], v189, v189 op_sel_hi:[0,0,0]
	v_mfma_scale_f32_16x16x128_f8f6f4 v[52:55], v[16:23], v[198:205], v[52:55], v189, v189 op_sel_hi:[0,0,0]
	v_mfma_scale_f32_16x16x128_f8f6f4 v[48:51], v[24:31], v[198:205], v[48:51], v189, v189 op_sel_hi:[0,0,0]
	v_mfma_scale_f32_16x16x128_f8f6f4 v[44:47], v[16:23], v[206:213], v[44:47], v189, v189 op_sel_hi:[0,0,0]
	v_mfma_scale_f32_16x16x128_f8f6f4 v[40:43], v[24:31], v[206:213], v[40:43], v189, v189 op_sel_hi:[0,0,0]
	v_mfma_scale_f32_16x16x128_f8f6f4 v[36:39], v[16:23], v[214:221], v[36:39], v189, v189 op_sel_hi:[0,0,0]
	v_mfma_scale_f32_16x16x128_f8f6f4 v[32:35], v[24:31], v[214:221], v[32:35], v189, v189 op_sel_hi:[0,0,0]
	s_setprio 0
	s_barrier
	s_add_i32 s71, s71, 2
	s_add_u32 s62, s62, 0x100
	s_addc_u32 s63, s63, 0
	s_add_u32 s65, s65, 0x100
	s_addc_u32 s70, s70, 0
	s_cmp_gt_u32 s71, 13
	s_cbranch_scc0 .LBB0_349
	s_and_b64 vcc, exec, s[18:19]
	s_cbranch_vccz .LBB0_352
	s_barrier

.LBB0_656:
	v_add_u32_e32 v1, s69, v177
	ds_read_b128 v[132:135], v1
	ds_read_b128 v[136:139], v1 offset:1024
	ds_read_b128 v[140:143], v1 offset:2048
	ds_read_b128 v[144:147], v1 offset:3072
	v_add_u32_e32 v1, s70, v177
	s_add_u32 s28, s26, s38
	ds_read_b128 v[180:183], v1
	ds_read_b128 v[184:187], v1 offset:1024
	ds_read_b128 v[188:191], v1 offset:2048
	ds_read_b128 v[192:195], v1 offset:3072
	s_addc_u32 s29, s27, s39
	s_add_u32 s28, s28, 0x100
	s_addc_u32 s29, s29, 0
	s_add_u32 s30, s73, s38
	s_addc_u32 s31, s74, s39
	s_cmpk_eq_i32 s38, 0xf00
	s_cselect_b32 s43, s19, s29
	s_cselect_b32 s42, s71, s28
	s_cselect_b32 s41, s17, s31
	s_cselect_b32 s40, s72, s30
	v_lshl_add_u64 v[2:3], v[170:171], 0, s[38:39]
	s_add_i32 m0, s50, 0xc000
	ds_read_b128 v[196:199], v179
	ds_read_b128 v[200:203], v179 offset:1024
	ds_read_b128 v[204:207], v179 offset:2048
	ds_read_b128 v[208:211], v179 offset:3072
	ds_read_b128 v[212:215], v179 offset:4096
	ds_read_b128 v[216:219], v179 offset:5120
	ds_read_b128 v[220:223], v179 offset:6144
	ds_read_b128 v[224:227], v179 offset:7168
	global_load_lds_dwordx4 v[2:3], off
	v_lshl_add_u64 v[2:3], v[172:173], 0, s[38:39]
	s_add_i32 m0, s50, 0xe000
	s_nop 0
	global_load_lds_dwordx4 v[2:3], off
	s_waitcnt vmcnt(8)
	s_waitcnt lgkmcnt(0)
	s_barrier
	s_setprio 1
	v_mfma_f32_16x16x32_bf16 v[128:131], v[132:135], v[196:199], v[128:131]
	v_mfma_f32_16x16x32_bf16 v[124:127], v[140:143], v[196:199], v[124:127]
	v_mfma_f32_16x16x32_bf16 v[112:115], v[132:135], v[204:207], v[112:115]
	v_mfma_f32_16x16x32_bf16 v[108:111], v[140:143], v[204:207], v[108:111]
	v_mfma_f32_16x16x32_bf16 v[96:99], v[132:135], v[212:215], v[96:99]
	v_mfma_f32_16x16x32_bf16 v[92:95], v[140:143], v[212:215], v[92:95]
	v_mfma_f32_16x16x32_bf16 v[80:83], v[132:135], v[220:223], v[80:83]
	v_mfma_f32_16x16x32_bf16 v[76:79], v[140:143], v[220:223], v[76:79]
	v_mfma_f32_16x16x32_bf16 v[128:131], v[136:139], v[200:203], v[128:131]
	v_mfma_f32_16x16x32_bf16 v[124:127], v[144:147], v[200:203], v[124:127]
	v_mfma_f32_16x16x32_bf16 v[112:115], v[136:139], v[208:211], v[112:115]
	v_mfma_f32_16x16x32_bf16 v[108:111], v[144:147], v[208:211], v[108:111]
	v_mfma_f32_16x16x32_bf16 v[96:99], v[136:139], v[216:219], v[96:99]
	v_mfma_f32_16x16x32_bf16 v[92:95], v[144:147], v[216:219], v[92:95]
	v_mfma_f32_16x16x32_bf16 v[80:83], v[136:139], v[224:227], v[80:83]
	v_mfma_f32_16x16x32_bf16 v[76:79], v[144:147], v[224:227], v[76:79]
	s_setprio 0
	s_setprio 1
	v_mfma_f32_16x16x32_bf16 v[120:123], v[180:183], v[196:199], v[120:123]
	v_mfma_f32_16x16x32_bf16 v[116:119], v[188:191], v[196:199], v[116:119]
	v_mfma_f32_16x16x32_bf16 v[104:107], v[180:183], v[204:207], v[104:107]
	v_mfma_f32_16x16x32_bf16 v[100:103], v[188:191], v[204:207], v[100:103]
	v_mfma_f32_16x16x32_bf16 v[88:91], v[180:183], v[212:215], v[88:91]
	v_mfma_f32_16x16x32_bf16 v[84:87], v[188:191], v[212:215], v[84:87]
	v_mfma_f32_16x16x32_bf16 v[72:75], v[180:183], v[220:223], v[72:75]
	v_mfma_f32_16x16x32_bf16 v[68:71], v[188:191], v[220:223], v[68:71]
	v_mfma_f32_16x16x32_bf16 v[120:123], v[184:187], v[200:203], v[120:123]
	v_mfma_f32_16x16x32_bf16 v[116:119], v[192:195], v[200:203], v[116:119]
	v_mfma_f32_16x16x32_bf16 v[104:107], v[184:187], v[208:211], v[104:107]
	v_mfma_f32_16x16x32_bf16 v[100:103], v[192:195], v[208:211], v[100:103]
	v_mfma_f32_16x16x32_bf16 v[88:91], v[184:187], v[216:219], v[88:91]
	v_mfma_f32_16x16x32_bf16 v[84:87], v[192:195], v[216:219], v[84:87]
	v_mfma_f32_16x16x32_bf16 v[72:75], v[184:187], v[224:227], v[72:75]
	v_mfma_f32_16x16x32_bf16 v[68:71], v[192:195], v[224:227], v[68:71]
	s_setprio 0
	s_barrier
	s_add_i32 s28, s69, s49
	v_lshl_add_u64 v[174:175], s[40:41], 0, v[150:151]
	s_mov_b32 m0, s28
	ds_read_b128 v[196:199], v179 offset:16384
	ds_read_b128 v[200:203], v179 offset:17408
	ds_read_b128 v[204:207], v179 offset:18432
	ds_read_b128 v[208:211], v179 offset:19456
	ds_read_b128 v[212:215], v179 offset:20480
	ds_read_b128 v[216:219], v179 offset:21504
	ds_read_b128 v[220:223], v179 offset:22528
	ds_read_b128 v[224:227], v179 offset:23552
	global_load_lds_dwordx4 v[174:175], off
	s_add_i32 m0, s28, 0x2000
	s_add_u32 s28, s40, 0x80000
	v_lshl_add_u64 v[228:229], s[40:41], 0, v[154:155]
	s_addc_u32 s29, s41, 0
	s_add_i32 s30, s70, s49
	global_load_lds_dwordx4 v[228:229], off
	v_lshl_add_u64 v[2:3], s[28:29], 0, v[150:151]
	s_mov_b32 m0, s30
	v_lshl_add_u64 v[230:231], s[42:43], 0, v[148:149]
	global_load_lds_dwordx4 v[2:3], off
	v_lshl_add_u64 v[2:3], s[28:29], 0, v[154:155]
	s_add_i32 m0, s30, 0x2000
	v_lshl_add_u64 v[232:233], s[42:43], 0, v[152:153]
	global_load_lds_dwordx4 v[2:3], off
	s_mov_b32 m0, s50
	s_nop 0
	global_load_lds_dwordx4 v[230:231], off
	s_mov_b32 m0, s51
	s_nop 0
	global_load_lds_dwordx4 v[232:233], off
	s_waitcnt vmcnt(8)
	s_waitcnt lgkmcnt(0)
	s_barrier
	s_setprio 1
	v_mfma_f32_16x16x32_bf16 v[64:67], v[132:135], v[196:199], v[64:67]
	v_mfma_f32_16x16x32_bf16 v[60:63], v[140:143], v[196:199], v[60:63]
	v_mfma_f32_16x16x32_bf16 v[48:51], v[132:135], v[204:207], v[48:51]
	v_mfma_f32_16x16x32_bf16 v[44:47], v[140:143], v[204:207], v[44:47]
	v_mfma_f32_16x16x32_bf16 v[32:35], v[132:135], v[212:215], v[32:35]
	v_mfma_f32_16x16x32_bf16 v[28:31], v[140:143], v[212:215], v[28:31]
	v_mfma_f32_16x16x32_bf16 v[16:19], v[132:135], v[220:223], v[16:19]
	v_mfma_f32_16x16x32_bf16 v[12:15], v[140:143], v[220:223], v[12:15]
	v_mfma_f32_16x16x32_bf16 v[64:67], v[136:139], v[200:203], v[64:67]
	v_mfma_f32_16x16x32_bf16 v[60:63], v[144:147], v[200:203], v[60:63]
	v_mfma_f32_16x16x32_bf16 v[48:51], v[136:139], v[208:211], v[48:51]
	v_mfma_f32_16x16x32_bf16 v[44:47], v[144:147], v[208:211], v[44:47]
	v_mfma_f32_16x16x32_bf16 v[32:35], v[136:139], v[216:219], v[32:35]
	v_mfma_f32_16x16x32_bf16 v[28:31], v[144:147], v[216:219], v[28:31]
	v_mfma_f32_16x16x32_bf16 v[16:19], v[136:139], v[224:227], v[16:19]
	v_mfma_f32_16x16x32_bf16 v[12:15], v[144:147], v[224:227], v[12:15]
	s_setprio 0
	s_setprio 1
	v_mfma_f32_16x16x32_bf16 v[56:59], v[180:183], v[196:199], v[56:59]
	v_mfma_f32_16x16x32_bf16 v[52:55], v[188:191], v[196:199], v[52:55]
	v_mfma_f32_16x16x32_bf16 v[40:43], v[180:183], v[204:207], v[40:43]
	v_mfma_f32_16x16x32_bf16 v[36:39], v[188:191], v[204:207], v[36:39]
	v_mfma_f32_16x16x32_bf16 v[24:27], v[180:183], v[212:215], v[24:27]
	v_mfma_f32_16x16x32_bf16 v[20:23], v[188:191], v[212:215], v[20:23]
	v_mfma_f32_16x16x32_bf16 v[8:11], v[180:183], v[220:223], v[8:11]
	v_mfma_f32_16x16x32_bf16 v[2:5], v[188:191], v[220:223], v[4:7]
	v_mfma_f32_16x16x32_bf16 v[56:59], v[184:187], v[200:203], v[56:59]
	v_mfma_f32_16x16x32_bf16 v[52:55], v[192:195], v[200:203], v[52:55]
	v_mfma_f32_16x16x32_bf16 v[40:43], v[184:187], v[208:211], v[40:43]
	v_mfma_f32_16x16x32_bf16 v[36:39], v[192:195], v[208:211], v[36:39]
	v_mfma_f32_16x16x32_bf16 v[24:27], v[184:187], v[216:219], v[24:27]
	v_mfma_f32_16x16x32_bf16 v[20:23], v[192:195], v[216:219], v[20:23]
	v_mfma_f32_16x16x32_bf16 v[8:11], v[184:187], v[224:227], v[8:11]
	v_mfma_f32_16x16x32_bf16 v[2:5], v[192:195], v[224:227], v[2:5]
	s_setprio 0
	s_barrier
	s_add_i32 s30, 0, 0x18000
	v_add_u32_e32 v1, s30, v177
	s_add_i32 s31, 0, 0x1c000
	ds_read_b128 v[132:135], v1
	ds_read_b128 v[136:139], v1 offset:1024
	ds_read_b128 v[140:143], v1 offset:2048
	ds_read_b128 v[144:147], v1 offset:3072
	v_add_u32_e32 v1, s31, v177
	ds_read_b128 v[180:183], v1
	ds_read_b128 v[184:187], v1 offset:1024
	ds_read_b128 v[188:191], v1 offset:2048
	ds_read_b128 v[192:195], v1 offset:3072
	s_add_u32 s28, s42, 0x80000
	s_addc_u32 s29, s43, 0
	s_mov_b32 m0, s62
	v_lshl_add_u64 v[6:7], s[28:29], 0, v[148:149]
	ds_read_b128 v[196:199], v179 offset:32768
	ds_read_b128 v[200:203], v179 offset:33792
	ds_read_b128 v[204:207], v179 offset:34816
	ds_read_b128 v[208:211], v179 offset:35840
	ds_read_b128 v[212:215], v179 offset:36864
	ds_read_b128 v[216:219], v179 offset:37888
	ds_read_b128 v[220:223], v179 offset:38912
	ds_read_b128 v[224:227], v179 offset:39936
	global_load_lds_dwordx4 v[6:7], off
	v_lshl_add_u64 v[6:7], s[28:29], 0, v[152:153]
	s_mov_b32 m0, s63
	s_nop 0
	global_load_lds_dwordx4 v[6:7], off
	s_waitcnt vmcnt(8)
	s_waitcnt lgkmcnt(0)
	s_barrier
	s_setprio 1
	v_mfma_f32_16x16x32_bf16 v[128:131], v[132:135], v[196:199], v[128:131]
	v_mfma_f32_16x16x32_bf16 v[124:127], v[140:143], v[196:199], v[124:127]
	v_mfma_f32_16x16x32_bf16 v[112:115], v[132:135], v[204:207], v[112:115]
	v_mfma_f32_16x16x32_bf16 v[108:111], v[140:143], v[204:207], v[108:111]
	v_mfma_f32_16x16x32_bf16 v[96:99], v[132:135], v[212:215], v[96:99]
	v_mfma_f32_16x16x32_bf16 v[92:95], v[140:143], v[212:215], v[92:95]
	v_mfma_f32_16x16x32_bf16 v[80:83], v[132:135], v[220:223], v[80:83]
	v_mfma_f32_16x16x32_bf16 v[76:79], v[140:143], v[220:223], v[76:79]
	v_mfma_f32_16x16x32_bf16 v[128:131], v[136:139], v[200:203], v[128:131]
	v_mfma_f32_16x16x32_bf16 v[124:127], v[144:147], v[200:203], v[124:127]
	v_mfma_f32_16x16x32_bf16 v[112:115], v[136:139], v[208:211], v[112:115]
	v_mfma_f32_16x16x32_bf16 v[108:111], v[144:147], v[208:211], v[108:111]
	v_mfma_f32_16x16x32_bf16 v[96:99], v[136:139], v[216:219], v[96:99]
	v_mfma_f32_16x16x32_bf16 v[92:95], v[144:147], v[216:219], v[92:95]
	v_mfma_f32_16x16x32_bf16 v[80:83], v[136:139], v[224:227], v[80:83]
	v_mfma_f32_16x16x32_bf16 v[76:79], v[144:147], v[224:227], v[76:79]
	s_setprio 0
	s_setprio 1
	v_mfma_f32_16x16x32_bf16 v[120:123], v[180:183], v[196:199], v[120:123]
	v_mfma_f32_16x16x32_bf16 v[116:119], v[188:191], v[196:199], v[116:119]
	v_mfma_f32_16x16x32_bf16 v[104:107], v[180:183], v[204:207], v[104:107]
	v_mfma_f32_16x16x32_bf16 v[100:103], v[188:191], v[204:207], v[100:103]
	v_mfma_f32_16x16x32_bf16 v[88:91], v[180:183], v[212:215], v[88:91]
	v_mfma_f32_16x16x32_bf16 v[84:87], v[188:191], v[212:215], v[84:87]
	v_mfma_f32_16x16x32_bf16 v[72:75], v[180:183], v[220:223], v[72:75]
	v_mfma_f32_16x16x32_bf16 v[68:71], v[188:191], v[220:223], v[68:71]
	v_mfma_f32_16x16x32_bf16 v[120:123], v[184:187], v[200:203], v[120:123]
	v_mfma_f32_16x16x32_bf16 v[116:119], v[192:195], v[200:203], v[116:119]
	v_mfma_f32_16x16x32_bf16 v[104:107], v[184:187], v[208:211], v[104:107]
	v_mfma_f32_16x16x32_bf16 v[100:103], v[192:195], v[208:211], v[100:103]
	v_mfma_f32_16x16x32_bf16 v[88:91], v[184:187], v[216:219], v[88:91]
	v_mfma_f32_16x16x32_bf16 v[84:87], v[192:195], v[216:219], v[84:87]
	v_mfma_f32_16x16x32_bf16 v[72:75], v[184:187], v[224:227], v[72:75]
	v_mfma_f32_16x16x32_bf16 v[68:71], v[192:195], v[224:227], v[68:71]
	s_setprio 0
	s_barrier
	s_add_i32 s28, s30, s49
	v_lshl_add_u64 v[6:7], v[174:175], 0, s[12:13]
	s_mov_b32 m0, s28
	ds_read_b128 v[196:199], v179 offset:49152
	ds_read_b128 v[200:203], v179 offset:50176
	ds_read_b128 v[204:207], v179 offset:51200
	ds_read_b128 v[208:211], v179 offset:52224
	ds_read_b128 v[212:215], v179 offset:53248
	ds_read_b128 v[216:219], v179 offset:54272
	ds_read_b128 v[220:223], v179 offset:55296
	ds_read_b128 v[224:227], v179 offset:56320
	global_load_lds_dwordx4 v[6:7], off
	s_add_i32 m0, s28, 0x2000
	s_add_u32 s28, s40, 0x80080
	v_lshl_add_u64 v[6:7], v[228:229], 0, s[12:13]
	s_addc_u32 s29, s41, 0
	s_add_i32 s30, s31, s49
	global_load_lds_dwordx4 v[6:7], off
	v_lshl_add_u64 v[6:7], s[28:29], 0, v[150:151]
	s_mov_b32 m0, s30
	s_nop 0
	global_load_lds_dwordx4 v[6:7], off
	v_lshl_add_u64 v[6:7], s[28:29], 0, v[154:155]
	s_add_i32 m0, s30, 0x2000
	s_nop 0
	global_load_lds_dwordx4 v[6:7], off
	v_lshl_add_u64 v[6:7], v[230:231], 0, s[12:13]
	s_mov_b32 m0, s65
	s_nop 0
	global_load_lds_dwordx4 v[6:7], off
	v_lshl_add_u64 v[6:7], v[232:233], 0, s[12:13]
	s_mov_b32 m0, s66
	s_nop 0
	global_load_lds_dwordx4 v[6:7], off
	s_waitcnt vmcnt(8)
	s_waitcnt lgkmcnt(0)
	s_barrier
	s_setprio 1
	v_mfma_f32_16x16x32_bf16 v[64:67], v[132:135], v[196:199], v[64:67]
	v_mfma_f32_16x16x32_bf16 v[60:63], v[140:143], v[196:199], v[60:63]
	v_mfma_f32_16x16x32_bf16 v[48:51], v[132:135], v[204:207], v[48:51]
	v_mfma_f32_16x16x32_bf16 v[44:47], v[140:143], v[204:207], v[44:47]
	v_mfma_f32_16x16x32_bf16 v[32:35], v[132:135], v[212:215], v[32:35]
	v_mfma_f32_16x16x32_bf16 v[28:31], v[140:143], v[212:215], v[28:31]
	v_mfma_f32_16x16x32_bf16 v[16:19], v[132:135], v[220:223], v[16:19]
	v_mfma_f32_16x16x32_bf16 v[12:15], v[140:143], v[220:223], v[12:15]
	v_mfma_f32_16x16x32_bf16 v[64:67], v[136:139], v[200:203], v[64:67]
	v_mfma_f32_16x16x32_bf16 v[60:63], v[144:147], v[200:203], v[60:63]
	v_mfma_f32_16x16x32_bf16 v[48:51], v[136:139], v[208:211], v[48:51]
	v_mfma_f32_16x16x32_bf16 v[44:47], v[144:147], v[208:211], v[44:47]
	v_mfma_f32_16x16x32_bf16 v[32:35], v[136:139], v[216:219], v[32:35]
	v_mfma_f32_16x16x32_bf16 v[28:31], v[144:147], v[216:219], v[28:31]
	v_mfma_f32_16x16x32_bf16 v[16:19], v[136:139], v[224:227], v[16:19]
	v_mfma_f32_16x16x32_bf16 v[12:15], v[144:147], v[224:227], v[12:15]
	s_setprio 0
	s_setprio 1
	v_mfma_f32_16x16x32_bf16 v[56:59], v[180:183], v[196:199], v[56:59]
	v_mfma_f32_16x16x32_bf16 v[52:55], v[188:191], v[196:199], v[52:55]
	v_mfma_f32_16x16x32_bf16 v[40:43], v[180:183], v[204:207], v[40:43]
	v_mfma_f32_16x16x32_bf16 v[36:39], v[188:191], v[204:207], v[36:39]
	v_mfma_f32_16x16x32_bf16 v[24:27], v[180:183], v[212:215], v[24:27]
	v_mfma_f32_16x16x32_bf16 v[20:23], v[188:191], v[212:215], v[20:23]
	v_mfma_f32_16x16x32_bf16 v[6:9], v[180:183], v[220:223], v[8:11]
	v_mfma_f32_16x16x32_bf16 v[2:5], v[188:191], v[220:223], v[2:5]
	v_mfma_f32_16x16x32_bf16 v[56:59], v[184:187], v[200:203], v[56:59]
	v_mfma_f32_16x16x32_bf16 v[52:55], v[192:195], v[200:203], v[52:55]
	v_mfma_f32_16x16x32_bf16 v[40:43], v[184:187], v[208:211], v[40:43]
	v_mfma_f32_16x16x32_bf16 v[36:39], v[192:195], v[208:211], v[36:39]
	v_mfma_f32_16x16x32_bf16 v[24:27], v[184:187], v[216:219], v[24:27]
	v_mfma_f32_16x16x32_bf16 v[20:23], v[192:195], v[216:219], v[20:23]
	v_mfma_f32_16x16x32_bf16 v[8:11], v[184:187], v[224:227], v[6:9]
	v_mfma_f32_16x16x32_bf16 v[4:7], v[192:195], v[224:227], v[2:5]
	s_setprio 0
	s_barrier
	s_add_i32 s75, s75, 2
	s_add_u32 s38, s38, 0x100
	s_addc_u32 s39, s39, 0
	s_cmp_gt_u32 s75, 29
	s_cbranch_scc1 .LBB0_659

.LBB0_738:
	ds_read_b128 v[16:19], v189
	ds_read_b128 v[20:23], v189 offset:1024
	ds_read_b128 v[24:27], v189 offset:2048
	ds_read_b128 v[28:31], v189 offset:3072
	ds_read_b128 v[0:3], v190
	ds_read_b128 v[4:7], v190 offset:1024
	ds_read_b128 v[8:11], v190 offset:2048
	ds_read_b128 v[12:15], v190 offset:3072
	s_add_u32 s28, s62, 0xfffc0080
	s_addc_u32 s29, s63, -1
	s_cmp_eq_u32 s87, 12
	s_cselect_b32 s67, s47, s29
	s_cselect_b32 s66, s83, s28
	s_cselect_b32 s65, s45, s86
	s_cselect_b32 s64, s84, s85
	v_lshl_add_u64 v[218:219], s[62:63], 0, v[170:171]
	s_add_i32 m0, s61, 0xc000
	ds_read_b128 v[178:181], v191
	ds_read_b128 v[182:185], v191 offset:1024
	ds_read_b128 v[194:197], v191 offset:2048
	ds_read_b128 v[198:201], v191 offset:3072
	ds_read_b128 v[202:205], v191 offset:4096
	ds_read_b128 v[206:209], v191 offset:5120
	ds_read_b128 v[210:213], v191 offset:6144
	ds_read_b128 v[214:217], v191 offset:7168
	global_load_lds_dwordx4 v[218:219], off
	v_lshl_add_u64 v[218:219], s[62:63], 0, v[172:173]
	s_add_i32 m0, s61, 0xe000
	s_nop 0
	global_load_lds_dwordx4 v[218:219], off
	s_waitcnt vmcnt(8)
	s_waitcnt lgkmcnt(0)
	s_barrier
	s_setprio 1
	v_mfma_scale_f32_16x16x128_f8f6f4 v[156:159], v[16:23], v[178:185], v[156:159], v192, v192 op_sel_hi:[0,0,0]
	v_mfma_scale_f32_16x16x128_f8f6f4 v[152:155], v[24:31], v[178:185], v[152:155], v192, v192 op_sel_hi:[0,0,0]
	v_mfma_scale_f32_16x16x128_f8f6f4 v[148:151], v[16:23], v[194:201], v[148:151], v192, v192 op_sel_hi:[0,0,0]
	v_mfma_scale_f32_16x16x128_f8f6f4 v[144:147], v[24:31], v[194:201], v[144:147], v192, v192 op_sel_hi:[0,0,0]
	v_mfma_scale_f32_16x16x128_f8f6f4 v[140:143], v[16:23], v[202:209], v[140:143], v192, v192 op_sel_hi:[0,0,0]
	v_mfma_scale_f32_16x16x128_f8f6f4 v[136:139], v[24:31], v[202:209], v[136:139], v192, v192 op_sel_hi:[0,0,0]
	v_mfma_scale_f32_16x16x128_f8f6f4 v[132:135], v[16:23], v[210:217], v[132:135], v192, v192 op_sel_hi:[0,0,0]
	v_mfma_scale_f32_16x16x128_f8f6f4 v[128:131], v[24:31], v[210:217], v[128:131], v192, v192 op_sel_hi:[0,0,0]
	s_setprio 0
	s_setprio 1
	v_mfma_scale_f32_16x16x128_f8f6f4 v[100:103], v[0:7], v[178:185], v[100:103], v192, v192 op_sel_hi:[0,0,0]
	v_mfma_scale_f32_16x16x128_f8f6f4 v[96:99], v[8:15], v[178:185], v[96:99], v192, v192 op_sel_hi:[0,0,0]
	v_mfma_scale_f32_16x16x128_f8f6f4 v[84:87], v[0:7], v[194:201], v[84:87], v192, v192 op_sel_hi:[0,0,0]
	v_mfma_scale_f32_16x16x128_f8f6f4 v[80:83], v[8:15], v[194:201], v[80:83], v192, v192 op_sel_hi:[0,0,0]
	v_mfma_scale_f32_16x16x128_f8f6f4 v[76:79], v[0:7], v[202:209], v[76:79], v192, v192 op_sel_hi:[0,0,0]
	v_mfma_scale_f32_16x16x128_f8f6f4 v[72:75], v[8:15], v[202:209], v[72:75], v192, v192 op_sel_hi:[0,0,0]
	v_mfma_scale_f32_16x16x128_f8f6f4 v[68:71], v[0:7], v[210:217], v[68:71], v192, v192 op_sel_hi:[0,0,0]
	v_mfma_scale_f32_16x16x128_f8f6f4 v[64:67], v[8:15], v[210:217], v[64:67], v192, v192 op_sel_hi:[0,0,0]
	s_setprio 0
	s_barrier
	s_add_i32 s28, s80, s23
	v_lshl_add_u64 v[178:179], s[64:65], 0, v[162:163]
	s_mov_b32 m0, s28
	ds_read_b128 v[194:197], v191 offset:16384
	ds_read_b128 v[198:201], v191 offset:17408
	ds_read_b128 v[202:205], v191 offset:18432
	ds_read_b128 v[206:209], v191 offset:19456
	ds_read_b128 v[210:213], v191 offset:20480
	ds_read_b128 v[214:217], v191 offset:21504
	ds_read_b128 v[218:221], v191 offset:22528
	ds_read_b128 v[222:225], v191 offset:23552
	global_load_lds_dwordx4 v[178:179], off
	s_add_i32 m0, s28, 0x2000
	s_add_u32 s28, s64, 0x40000
	v_lshl_add_u64 v[180:181], s[64:65], 0, v[166:167]
	s_addc_u32 s29, s65, 0
	s_add_i32 s30, s81, s23
	global_load_lds_dwordx4 v[180:181], off
	v_lshl_add_u64 v[182:183], s[28:29], 0, v[162:163]
	s_mov_b32 m0, s30
	v_lshl_add_u64 v[184:185], s[66:67], 0, v[164:165]
	global_load_lds_dwordx4 v[182:183], off
	v_lshl_add_u64 v[182:183], s[28:29], 0, v[166:167]
	s_add_i32 m0, s30, 0x2000
	s_nop 0
	global_load_lds_dwordx4 v[182:183], off
	v_lshl_add_u64 v[182:183], s[66:67], 0, v[160:161]
	s_mov_b32 m0, s61
	s_nop 0
	global_load_lds_dwordx4 v[182:183], off
	s_mov_b32 m0, s72
	s_nop 0
	global_load_lds_dwordx4 v[184:185], off
	s_waitcnt vmcnt(8)
	s_waitcnt lgkmcnt(0)
	s_barrier
	s_setprio 1
	v_mfma_scale_f32_16x16x128_f8f6f4 v[124:127], v[16:23], v[194:201], v[124:127], v192, v192 op_sel_hi:[0,0,0]
	v_mfma_scale_f32_16x16x128_f8f6f4 v[120:123], v[24:31], v[194:201], v[120:123], v192, v192 op_sel_hi:[0,0,0]
	v_mfma_scale_f32_16x16x128_f8f6f4 v[116:119], v[16:23], v[202:209], v[116:119], v192, v192 op_sel_hi:[0,0,0]
	v_mfma_scale_f32_16x16x128_f8f6f4 v[112:115], v[24:31], v[202:209], v[112:115], v192, v192 op_sel_hi:[0,0,0]
	v_mfma_scale_f32_16x16x128_f8f6f4 v[108:111], v[16:23], v[210:217], v[108:111], v192, v192 op_sel_hi:[0,0,0]
	v_mfma_scale_f32_16x16x128_f8f6f4 v[104:107], v[24:31], v[210:217], v[104:107], v192, v192 op_sel_hi:[0,0,0]
	v_mfma_scale_f32_16x16x128_f8f6f4 v[92:95], v[16:23], v[218:225], v[92:95], v192, v192 op_sel_hi:[0,0,0]
	v_mfma_scale_f32_16x16x128_f8f6f4 v[88:91], v[24:31], v[218:225], v[88:91], v192, v192 op_sel_hi:[0,0,0]
	s_setprio 0
	s_setprio 1
	v_mfma_scale_f32_16x16x128_f8f6f4 v[60:63], v[0:7], v[194:201], v[60:63], v192, v192 op_sel_hi:[0,0,0]
	v_mfma_scale_f32_16x16x128_f8f6f4 v[56:59], v[8:15], v[194:201], v[56:59], v192, v192 op_sel_hi:[0,0,0]
	v_mfma_scale_f32_16x16x128_f8f6f4 v[52:55], v[0:7], v[202:209], v[52:55], v192, v192 op_sel_hi:[0,0,0]
	v_mfma_scale_f32_16x16x128_f8f6f4 v[48:51], v[8:15], v[202:209], v[48:51], v192, v192 op_sel_hi:[0,0,0]
	v_mfma_scale_f32_16x16x128_f8f6f4 v[44:47], v[0:7], v[210:217], v[44:47], v192, v192 op_sel_hi:[0,0,0]
	v_mfma_scale_f32_16x16x128_f8f6f4 v[40:43], v[8:15], v[210:217], v[40:43], v192, v192 op_sel_hi:[0,0,0]
	v_mfma_scale_f32_16x16x128_f8f6f4 v[36:39], v[0:7], v[218:225], v[36:39], v192, v192 op_sel_hi:[0,0,0]
	v_mfma_scale_f32_16x16x128_f8f6f4 v[32:35], v[8:15], v[218:225], v[32:35], v192, v192 op_sel_hi:[0,0,0]
	s_setprio 0
	s_barrier
	s_add_i32 s30, 0, 0x18000
	s_add_i32 s31, 0, 0x1c000
	v_add_u32_e32 v12, s30, v187
	v_add_u32_e32 v28, s31, v187
	ds_read_b128 v[0:3], v12
	ds_read_b128 v[4:7], v12 offset:1024
	ds_read_b128 v[8:11], v12 offset:2048
	ds_read_b128 v[12:15], v12 offset:3072
	ds_read_b128 v[16:19], v28
	ds_read_b128 v[20:23], v28 offset:1024
	ds_read_b128 v[24:27], v28 offset:2048
	ds_read_b128 v[28:31], v28 offset:3072
	s_add_u32 s28, s66, 0x40000
	s_addc_u32 s29, s67, 0
	s_mov_b32 m0, s73
	v_lshl_add_u64 v[226:227], s[28:29], 0, v[160:161]
	ds_read_b128 v[194:197], v191 offset:32768
	ds_read_b128 v[198:201], v191 offset:33792
	ds_read_b128 v[202:205], v191 offset:34816
	ds_read_b128 v[206:209], v191 offset:35840
	ds_read_b128 v[210:213], v191 offset:36864
	ds_read_b128 v[214:217], v191 offset:37888
	ds_read_b128 v[218:221], v191 offset:38912
	ds_read_b128 v[222:225], v191 offset:39936
	global_load_lds_dwordx4 v[226:227], off
	v_lshl_add_u64 v[226:227], s[28:29], 0, v[164:165]
	s_mov_b32 m0, s74
	s_nop 0
	global_load_lds_dwordx4 v[226:227], off
	s_waitcnt vmcnt(8)
	s_waitcnt lgkmcnt(0)
	s_barrier
	s_setprio 1
	v_mfma_scale_f32_16x16x128_f8f6f4 v[156:159], v[0:7], v[194:201], v[156:159], v192, v192 op_sel_hi:[0,0,0]
	v_mfma_scale_f32_16x16x128_f8f6f4 v[152:155], v[8:15], v[194:201], v[152:155], v192, v192 op_sel_hi:[0,0,0]
	v_mfma_scale_f32_16x16x128_f8f6f4 v[148:151], v[0:7], v[202:209], v[148:151], v192, v192 op_sel_hi:[0,0,0]
	v_mfma_scale_f32_16x16x128_f8f6f4 v[144:147], v[8:15], v[202:209], v[144:147], v192, v192 op_sel_hi:[0,0,0]
	v_mfma_scale_f32_16x16x128_f8f6f4 v[140:143], v[0:7], v[210:217], v[140:143], v192, v192 op_sel_hi:[0,0,0]
	v_mfma_scale_f32_16x16x128_f8f6f4 v[136:139], v[8:15], v[210:217], v[136:139], v192, v192 op_sel_hi:[0,0,0]
	v_mfma_scale_f32_16x16x128_f8f6f4 v[132:135], v[0:7], v[218:225], v[132:135], v192, v192 op_sel_hi:[0,0,0]
	v_mfma_scale_f32_16x16x128_f8f6f4 v[128:131], v[8:15], v[218:225], v[128:131], v192, v192 op_sel_hi:[0,0,0]
	s_setprio 0
	s_setprio 1
	v_mfma_scale_f32_16x16x128_f8f6f4 v[100:103], v[16:23], v[194:201], v[100:103], v192, v192 op_sel_hi:[0,0,0]
	v_mfma_scale_f32_16x16x128_f8f6f4 v[96:99], v[24:31], v[194:201], v[96:99], v192, v192 op_sel_hi:[0,0,0]
	v_mfma_scale_f32_16x16x128_f8f6f4 v[84:87], v[16:23], v[202:209], v[84:87], v192, v192 op_sel_hi:[0,0,0]
	v_mfma_scale_f32_16x16x128_f8f6f4 v[80:83], v[24:31], v[202:209], v[80:83], v192, v192 op_sel_hi:[0,0,0]
	v_mfma_scale_f32_16x16x128_f8f6f4 v[76:79], v[16:23], v[210:217], v[76:79], v192, v192 op_sel_hi:[0,0,0]
	v_mfma_scale_f32_16x16x128_f8f6f4 v[72:75], v[24:31], v[210:217], v[72:75], v192, v192 op_sel_hi:[0,0,0]
	v_mfma_scale_f32_16x16x128_f8f6f4 v[68:71], v[16:23], v[218:225], v[68:71], v192, v192 op_sel_hi:[0,0,0]
	v_mfma_scale_f32_16x16x128_f8f6f4 v[64:67], v[24:31], v[218:225], v[64:67], v192, v192 op_sel_hi:[0,0,0]
	s_setprio 0
	s_barrier
	s_add_i32 s28, s30, s23
	v_lshl_add_u64 v[178:179], v[178:179], 0, s[12:13]
	s_mov_b32 m0, s28
	ds_read_b128 v[194:197], v191 offset:49152
	ds_read_b128 v[198:201], v191 offset:50176
	ds_read_b128 v[202:205], v191 offset:51200
	ds_read_b128 v[206:209], v191 offset:52224
	ds_read_b128 v[210:213], v191 offset:53248
	ds_read_b128 v[214:217], v191 offset:54272
	ds_read_b128 v[218:221], v191 offset:55296
	ds_read_b128 v[222:225], v191 offset:56320
	global_load_lds_dwordx4 v[178:179], off
	s_add_i32 m0, s28, 0x2000
	s_add_u32 s28, s64, 0x40080
	v_lshl_add_u64 v[178:179], v[180:181], 0, s[12:13]
	s_addc_u32 s29, s65, 0
	s_add_i32 s30, s31, s23
	global_load_lds_dwordx4 v[178:179], off
	v_lshl_add_u64 v[178:179], s[28:29], 0, v[162:163]
	s_mov_b32 m0, s30
	s_nop 0
	global_load_lds_dwordx4 v[178:179], off
	v_lshl_add_u64 v[178:179], s[28:29], 0, v[166:167]
	s_add_i32 m0, s30, 0x2000
	s_nop 0
	global_load_lds_dwordx4 v[178:179], off
	v_lshl_add_u64 v[178:179], v[182:183], 0, s[12:13]
	s_mov_b32 m0, s76
	s_nop 0
	global_load_lds_dwordx4 v[178:179], off
	v_lshl_add_u64 v[178:179], v[184:185], 0, s[12:13]
	s_mov_b32 m0, s77
	s_nop 0
	global_load_lds_dwordx4 v[178:179], off
	s_waitcnt vmcnt(8)
	s_waitcnt lgkmcnt(0)
	s_barrier
	s_setprio 1
	v_mfma_scale_f32_16x16x128_f8f6f4 v[124:127], v[0:7], v[194:201], v[124:127], v192, v192 op_sel_hi:[0,0,0]
	v_mfma_scale_f32_16x16x128_f8f6f4 v[120:123], v[8:15], v[194:201], v[120:123], v192, v192 op_sel_hi:[0,0,0]
	v_mfma_scale_f32_16x16x128_f8f6f4 v[116:119], v[0:7], v[202:209], v[116:119], v192, v192 op_sel_hi:[0,0,0]
	v_mfma_scale_f32_16x16x128_f8f6f4 v[112:115], v[8:15], v[202:209], v[112:115], v192, v192 op_sel_hi:[0,0,0]
	v_mfma_scale_f32_16x16x128_f8f6f4 v[108:111], v[0:7], v[210:217], v[108:111], v192, v192 op_sel_hi:[0,0,0]
	v_mfma_scale_f32_16x16x128_f8f6f4 v[104:107], v[8:15], v[210:217], v[104:107], v192, v192 op_sel_hi:[0,0,0]
	v_mfma_scale_f32_16x16x128_f8f6f4 v[92:95], v[0:7], v[218:225], v[92:95], v192, v192 op_sel_hi:[0,0,0]
	v_mfma_scale_f32_16x16x128_f8f6f4 v[88:91], v[8:15], v[218:225], v[88:91], v192, v192 op_sel_hi:[0,0,0]
	s_setprio 0
	s_setprio 1
	v_mfma_scale_f32_16x16x128_f8f6f4 v[60:63], v[16:23], v[194:201], v[60:63], v192, v192 op_sel_hi:[0,0,0]
	v_mfma_scale_f32_16x16x128_f8f6f4 v[56:59], v[24:31], v[194:201], v[56:59], v192, v192 op_sel_hi:[0,0,0]
	v_mfma_scale_f32_16x16x128_f8f6f4 v[52:55], v[16:23], v[202:209], v[52:55], v192, v192 op_sel_hi:[0,0,0]
	v_mfma_scale_f32_16x16x128_f8f6f4 v[48:51], v[24:31], v[202:209], v[48:51], v192, v192 op_sel_hi:[0,0,0]
	v_mfma_scale_f32_16x16x128_f8f6f4 v[44:47], v[16:23], v[210:217], v[44:47], v192, v192 op_sel_hi:[0,0,0]
	v_mfma_scale_f32_16x16x128_f8f6f4 v[40:43], v[24:31], v[210:217], v[40:43], v192, v192 op_sel_hi:[0,0,0]
	v_mfma_scale_f32_16x16x128_f8f6f4 v[36:39], v[16:23], v[218:225], v[36:39], v192, v192 op_sel_hi:[0,0,0]
	v_mfma_scale_f32_16x16x128_f8f6f4 v[32:35], v[24:31], v[218:225], v[32:35], v192, v192 op_sel_hi:[0,0,0]
	s_setprio 0
	s_barrier
	s_add_i32 s87, s87, 2
	s_add_u32 s62, s62, 0x100
	s_addc_u32 s63, s63, 0
	s_add_u32 s85, s85, 0x100
	s_addc_u32 s86, s86, 0
	s_cmp_gt_u32 s87, 13
	s_cbranch_scc0 .LBB0_738
	s_and_b64 vcc, exec, s[14:15]
	s_cbranch_vccz .LBB0_741
	s_barrier

.LBB0_818:
	v_add_u32_e32 v0, s51, v193
	v_add_u32_e32 v12, s58, v193
	s_add_u32 s28, s12, s26
	ds_read_b128 v[16:19], v0
	ds_read_b128 v[20:23], v0 offset:1024
	ds_read_b128 v[24:27], v0 offset:2048
	ds_read_b128 v[28:31], v0 offset:3072
	ds_read_b128 v[0:3], v12
	ds_read_b128 v[4:7], v12 offset:1024
	ds_read_b128 v[8:11], v12 offset:2048
	ds_read_b128 v[12:15], v12 offset:3072
	s_addc_u32 s29, s13, s27
	s_add_u32 s28, s28, 0x100
	s_addc_u32 s29, s29, 0
	s_add_u32 s30, s23, s26
	s_addc_u32 s31, s59, s27
	s_cmpk_eq_i32 s26, 0x700
	s_cselect_b32 s41, s19, s29
	s_cselect_b32 s40, s60, s28
	s_cselect_b32 s39, s17, s31
	s_cselect_b32 s38, s61, s30
	v_lshl_add_u64 v[220:221], v[178:179], 0, s[26:27]
	s_add_i32 m0, s43, 0xc000
	ds_read_b128 v[182:185], v194
	ds_read_b128 v[186:189], v194 offset:1024
	ds_read_b128 v[196:199], v194 offset:2048
	ds_read_b128 v[200:203], v194 offset:3072
	ds_read_b128 v[204:207], v194 offset:4096
	ds_read_b128 v[208:211], v194 offset:5120
	ds_read_b128 v[212:215], v194 offset:6144
	ds_read_b128 v[216:219], v194 offset:7168
	global_load_lds_dwordx4 v[220:221], off
	v_lshl_add_u64 v[220:221], v[180:181], 0, s[26:27]
	s_add_i32 m0, s43, 0xe000
	s_nop 0
	global_load_lds_dwordx4 v[220:221], off
	s_waitcnt vmcnt(8)
	s_waitcnt lgkmcnt(0)
	s_barrier
	s_setprio 1
	v_mfma_scale_f32_16x16x128_f8f6f4 v[156:159], v[16:23], v[182:189], v[156:159], v195, v195 op_sel_hi:[0,0,0]
	v_mfma_scale_f32_16x16x128_f8f6f4 v[152:155], v[24:31], v[182:189], v[152:155], v195, v195 op_sel_hi:[0,0,0]
	v_mfma_scale_f32_16x16x128_f8f6f4 v[148:151], v[16:23], v[196:203], v[148:151], v195, v195 op_sel_hi:[0,0,0]
	v_mfma_scale_f32_16x16x128_f8f6f4 v[144:147], v[24:31], v[196:203], v[144:147], v195, v195 op_sel_hi:[0,0,0]
	v_mfma_scale_f32_16x16x128_f8f6f4 v[140:143], v[16:23], v[204:211], v[140:143], v195, v195 op_sel_hi:[0,0,0]
	v_mfma_scale_f32_16x16x128_f8f6f4 v[136:139], v[24:31], v[204:211], v[136:139], v195, v195 op_sel_hi:[0,0,0]
	v_mfma_scale_f32_16x16x128_f8f6f4 v[132:135], v[16:23], v[212:219], v[132:135], v195, v195 op_sel_hi:[0,0,0]
	v_mfma_scale_f32_16x16x128_f8f6f4 v[128:131], v[24:31], v[212:219], v[128:131], v195, v195 op_sel_hi:[0,0,0]
	s_setprio 0
	s_setprio 1
	v_mfma_scale_f32_16x16x128_f8f6f4 v[92:95], v[0:7], v[182:189], v[92:95], v195, v195 op_sel_hi:[0,0,0]
	v_mfma_scale_f32_16x16x128_f8f6f4 v[88:91], v[8:15], v[182:189], v[88:91], v195, v195 op_sel_hi:[0,0,0]
	v_mfma_scale_f32_16x16x128_f8f6f4 v[84:87], v[0:7], v[196:203], v[84:87], v195, v195 op_sel_hi:[0,0,0]
	v_mfma_scale_f32_16x16x128_f8f6f4 v[80:83], v[8:15], v[196:203], v[80:83], v195, v195 op_sel_hi:[0,0,0]
	v_mfma_scale_f32_16x16x128_f8f6f4 v[76:79], v[0:7], v[204:211], v[76:79], v195, v195 op_sel_hi:[0,0,0]
	v_mfma_scale_f32_16x16x128_f8f6f4 v[72:75], v[8:15], v[204:211], v[72:75], v195, v195 op_sel_hi:[0,0,0]
	v_mfma_scale_f32_16x16x128_f8f6f4 v[68:71], v[0:7], v[212:219], v[68:71], v195, v195 op_sel_hi:[0,0,0]
	v_mfma_scale_f32_16x16x128_f8f6f4 v[64:67], v[8:15], v[212:219], v[64:67], v195, v195 op_sel_hi:[0,0,0]
	s_setprio 0
	s_barrier
	s_add_i32 s28, s51, s42
	v_lshl_add_u64 v[182:183], s[38:39], 0, v[162:163]
	s_mov_b32 m0, s28
	ds_read_b128 v[196:199], v194 offset:16384
	ds_read_b128 v[200:203], v194 offset:17408
	ds_read_b128 v[204:207], v194 offset:18432
	ds_read_b128 v[208:211], v194 offset:19456
	ds_read_b128 v[212:215], v194 offset:20480
	ds_read_b128 v[216:219], v194 offset:21504
	ds_read_b128 v[220:223], v194 offset:22528
	ds_read_b128 v[224:227], v194 offset:23552
	global_load_lds_dwordx4 v[182:183], off
	s_add_i32 m0, s28, 0x2000
	s_add_u32 s28, s38, 0x40000
	v_lshl_add_u64 v[184:185], s[38:39], 0, v[166:167]
	s_addc_u32 s29, s39, 0
	s_add_i32 s30, s58, s42
	global_load_lds_dwordx4 v[184:185], off
	v_lshl_add_u64 v[186:187], s[28:29], 0, v[162:163]
	s_mov_b32 m0, s30
	v_lshl_add_u64 v[188:189], s[40:41], 0, v[164:165]
	global_load_lds_dwordx4 v[186:187], off
	v_lshl_add_u64 v[186:187], s[28:29], 0, v[166:167]
	s_add_i32 m0, s30, 0x2000
	s_nop 0
	global_load_lds_dwordx4 v[186:187], off
	v_lshl_add_u64 v[186:187], s[40:41], 0, v[160:161]
	s_mov_b32 m0, s43
	s_nop 0
	global_load_lds_dwordx4 v[186:187], off
	s_mov_b32 m0, s44
	s_nop 0
	global_load_lds_dwordx4 v[188:189], off
	s_waitcnt vmcnt(8)
	s_waitcnt lgkmcnt(0)
	s_barrier
	s_setprio 1
	v_mfma_scale_f32_16x16x128_f8f6f4 v[124:127], v[16:23], v[196:203], v[124:127], v195, v195 op_sel_hi:[0,0,0]
	v_mfma_scale_f32_16x16x128_f8f6f4 v[120:123], v[24:31], v[196:203], v[120:123], v195, v195 op_sel_hi:[0,0,0]
	v_mfma_scale_f32_16x16x128_f8f6f4 v[116:119], v[16:23], v[204:211], v[116:119], v195, v195 op_sel_hi:[0,0,0]
	v_mfma_scale_f32_16x16x128_f8f6f4 v[112:115], v[24:31], v[204:211], v[112:115], v195, v195 op_sel_hi:[0,0,0]
	v_mfma_scale_f32_16x16x128_f8f6f4 v[108:111], v[16:23], v[212:219], v[108:111], v195, v195 op_sel_hi:[0,0,0]
	v_mfma_scale_f32_16x16x128_f8f6f4 v[104:107], v[24:31], v[212:219], v[104:107], v195, v195 op_sel_hi:[0,0,0]
	v_mfma_scale_f32_16x16x128_f8f6f4 v[100:103], v[16:23], v[220:227], v[100:103], v195, v195 op_sel_hi:[0,0,0]
	v_mfma_scale_f32_16x16x128_f8f6f4 v[96:99], v[24:31], v[220:227], v[96:99], v195, v195 op_sel_hi:[0,0,0]
	s_setprio 0
	s_setprio 1
	v_mfma_scale_f32_16x16x128_f8f6f4 v[60:63], v[0:7], v[196:203], v[60:63], v195, v195 op_sel_hi:[0,0,0]
	v_mfma_scale_f32_16x16x128_f8f6f4 v[56:59], v[8:15], v[196:203], v[56:59], v195, v195 op_sel_hi:[0,0,0]
	v_mfma_scale_f32_16x16x128_f8f6f4 v[52:55], v[0:7], v[204:211], v[52:55], v195, v195 op_sel_hi:[0,0,0]
	v_mfma_scale_f32_16x16x128_f8f6f4 v[48:51], v[8:15], v[204:211], v[48:51], v195, v195 op_sel_hi:[0,0,0]
	v_mfma_scale_f32_16x16x128_f8f6f4 v[44:47], v[0:7], v[212:219], v[44:47], v195, v195 op_sel_hi:[0,0,0]
	v_mfma_scale_f32_16x16x128_f8f6f4 v[40:43], v[8:15], v[212:219], v[40:43], v195, v195 op_sel_hi:[0,0,0]
	v_mfma_scale_f32_16x16x128_f8f6f4 v[36:39], v[0:7], v[220:227], v[36:39], v195, v195 op_sel_hi:[0,0,0]
	v_mfma_scale_f32_16x16x128_f8f6f4 v[32:35], v[8:15], v[220:227], v[32:35], v195, v195 op_sel_hi:[0,0,0]
	s_setprio 0
	s_barrier
	s_add_i32 s30, 0, 0x18000
	s_add_i32 s31, 0, 0x1c000
	v_add_u32_e32 v12, s30, v193
	v_add_u32_e32 v28, s31, v193
	ds_read_b128 v[0:3], v12
	ds_read_b128 v[4:7], v12 offset:1024
	ds_read_b128 v[8:11], v12 offset:2048
	ds_read_b128 v[12:15], v12 offset:3072
	ds_read_b128 v[16:19], v28
	ds_read_b128 v[20:23], v28 offset:1024
	ds_read_b128 v[24:27], v28 offset:2048
	ds_read_b128 v[28:31], v28 offset:3072
	s_add_u32 s28, s40, 0x40000
	s_addc_u32 s29, s41, 0
	s_mov_b32 m0, s45
	v_lshl_add_u64 v[228:229], s[28:29], 0, v[160:161]
	ds_read_b128 v[196:199], v194 offset:32768
	ds_read_b128 v[200:203], v194 offset:33792
	ds_read_b128 v[204:207], v194 offset:34816
	ds_read_b128 v[208:211], v194 offset:35840
	ds_read_b128 v[212:215], v194 offset:36864
	ds_read_b128 v[216:219], v194 offset:37888
	ds_read_b128 v[220:223], v194 offset:38912
	ds_read_b128 v[224:227], v194 offset:39936
	global_load_lds_dwordx4 v[228:229], off
	v_lshl_add_u64 v[228:229], s[28:29], 0, v[164:165]
	s_mov_b32 m0, s46
	s_nop 0
	global_load_lds_dwordx4 v[228:229], off
	s_waitcnt vmcnt(8)
	s_waitcnt lgkmcnt(0)
	s_barrier
	s_setprio 1
	v_mfma_scale_f32_16x16x128_f8f6f4 v[156:159], v[0:7], v[196:203], v[156:159], v195, v195 op_sel_hi:[0,0,0]
	v_mfma_scale_f32_16x16x128_f8f6f4 v[152:155], v[8:15], v[196:203], v[152:155], v195, v195 op_sel_hi:[0,0,0]
	v_mfma_scale_f32_16x16x128_f8f6f4 v[148:151], v[0:7], v[204:211], v[148:151], v195, v195 op_sel_hi:[0,0,0]
	v_mfma_scale_f32_16x16x128_f8f6f4 v[144:147], v[8:15], v[204:211], v[144:147], v195, v195 op_sel_hi:[0,0,0]
	v_mfma_scale_f32_16x16x128_f8f6f4 v[140:143], v[0:7], v[212:219], v[140:143], v195, v195 op_sel_hi:[0,0,0]
	v_mfma_scale_f32_16x16x128_f8f6f4 v[136:139], v[8:15], v[212:219], v[136:139], v195, v195 op_sel_hi:[0,0,0]
	v_mfma_scale_f32_16x16x128_f8f6f4 v[132:135], v[0:7], v[220:227], v[132:135], v195, v195 op_sel_hi:[0,0,0]
	v_mfma_scale_f32_16x16x128_f8f6f4 v[128:131], v[8:15], v[220:227], v[128:131], v195, v195 op_sel_hi:[0,0,0]
	s_setprio 0
	s_setprio 1
	v_mfma_scale_f32_16x16x128_f8f6f4 v[92:95], v[16:23], v[196:203], v[92:95], v195, v195 op_sel_hi:[0,0,0]
	v_mfma_scale_f32_16x16x128_f8f6f4 v[88:91], v[24:31], v[196:203], v[88:91], v195, v195 op_sel_hi:[0,0,0]
	v_mfma_scale_f32_16x16x128_f8f6f4 v[84:87], v[16:23], v[204:211], v[84:87], v195, v195 op_sel_hi:[0,0,0]
	v_mfma_scale_f32_16x16x128_f8f6f4 v[80:83], v[24:31], v[204:211], v[80:83], v195, v195 op_sel_hi:[0,0,0]
	v_mfma_scale_f32_16x16x128_f8f6f4 v[76:79], v[16:23], v[212:219], v[76:79], v195, v195 op_sel_hi:[0,0,0]
	v_mfma_scale_f32_16x16x128_f8f6f4 v[72:75], v[24:31], v[212:219], v[72:75], v195, v195 op_sel_hi:[0,0,0]
	v_mfma_scale_f32_16x16x128_f8f6f4 v[68:71], v[16:23], v[220:227], v[68:71], v195, v195 op_sel_hi:[0,0,0]
	v_mfma_scale_f32_16x16x128_f8f6f4 v[64:67], v[24:31], v[220:227], v[64:67], v195, v195 op_sel_hi:[0,0,0]
	s_setprio 0
	s_barrier
	s_add_i32 s28, s30, s42
	v_lshl_add_u64 v[182:183], v[182:183], 0, s[14:15]
	s_mov_b32 m0, s28
	ds_read_b128 v[196:199], v194 offset:49152
	ds_read_b128 v[200:203], v194 offset:50176
	ds_read_b128 v[204:207], v194 offset:51200
	ds_read_b128 v[208:211], v194 offset:52224
	ds_read_b128 v[212:215], v194 offset:53248
	ds_read_b128 v[216:219], v194 offset:54272
	ds_read_b128 v[220:223], v194 offset:55296
	ds_read_b128 v[224:227], v194 offset:56320
	global_load_lds_dwordx4 v[182:183], off
	s_add_i32 m0, s28, 0x2000
	s_add_u32 s28, s38, 0x40080
	v_lshl_add_u64 v[182:183], v[184:185], 0, s[14:15]
	s_addc_u32 s29, s39, 0
	s_add_i32 s30, s31, s42
	global_load_lds_dwordx4 v[182:183], off
	v_lshl_add_u64 v[182:183], s[28:29], 0, v[162:163]
	s_mov_b32 m0, s30
	s_nop 0
	global_load_lds_dwordx4 v[182:183], off
	v_lshl_add_u64 v[182:183], s[28:29], 0, v[166:167]
	s_add_i32 m0, s30, 0x2000
	s_nop 0
	global_load_lds_dwordx4 v[182:183], off
	v_lshl_add_u64 v[182:183], v[186:187], 0, s[14:15]
	s_mov_b32 m0, s49
	s_nop 0
	global_load_lds_dwordx4 v[182:183], off
	v_lshl_add_u64 v[182:183], v[188:189], 0, s[14:15]
	s_mov_b32 m0, s50
	s_nop 0
	global_load_lds_dwordx4 v[182:183], off
	s_waitcnt vmcnt(8)
	s_waitcnt lgkmcnt(0)
	s_barrier
	s_setprio 1
	v_mfma_scale_f32_16x16x128_f8f6f4 v[124:127], v[0:7], v[196:203], v[124:127], v195, v195 op_sel_hi:[0,0,0]
	v_mfma_scale_f32_16x16x128_f8f6f4 v[120:123], v[8:15], v[196:203], v[120:123], v195, v195 op_sel_hi:[0,0,0]
	v_mfma_scale_f32_16x16x128_f8f6f4 v[116:119], v[0:7], v[204:211], v[116:119], v195, v195 op_sel_hi:[0,0,0]
	v_mfma_scale_f32_16x16x128_f8f6f4 v[112:115], v[8:15], v[204:211], v[112:115], v195, v195 op_sel_hi:[0,0,0]
	v_mfma_scale_f32_16x16x128_f8f6f4 v[108:111], v[0:7], v[212:219], v[108:111], v195, v195 op_sel_hi:[0,0,0]
	v_mfma_scale_f32_16x16x128_f8f6f4 v[104:107], v[8:15], v[212:219], v[104:107], v195, v195 op_sel_hi:[0,0,0]
	v_mfma_scale_f32_16x16x128_f8f6f4 v[100:103], v[0:7], v[220:227], v[100:103], v195, v195 op_sel_hi:[0,0,0]
	v_mfma_scale_f32_16x16x128_f8f6f4 v[96:99], v[8:15], v[220:227], v[96:99], v195, v195 op_sel_hi:[0,0,0]
	s_setprio 0
	s_setprio 1
	v_mfma_scale_f32_16x16x128_f8f6f4 v[60:63], v[16:23], v[196:203], v[60:63], v195, v195 op_sel_hi:[0,0,0]
	v_mfma_scale_f32_16x16x128_f8f6f4 v[56:59], v[24:31], v[196:203], v[56:59], v195, v195 op_sel_hi:[0,0,0]
	v_mfma_scale_f32_16x16x128_f8f6f4 v[52:55], v[16:23], v[204:211], v[52:55], v195, v195 op_sel_hi:[0,0,0]
	v_mfma_scale_f32_16x16x128_f8f6f4 v[48:51], v[24:31], v[204:211], v[48:51], v195, v195 op_sel_hi:[0,0,0]
	v_mfma_scale_f32_16x16x128_f8f6f4 v[44:47], v[16:23], v[212:219], v[44:47], v195, v195 op_sel_hi:[0,0,0]
	v_mfma_scale_f32_16x16x128_f8f6f4 v[40:43], v[24:31], v[212:219], v[40:43], v195, v195 op_sel_hi:[0,0,0]
	v_mfma_scale_f32_16x16x128_f8f6f4 v[36:39], v[16:23], v[220:227], v[36:39], v195, v195 op_sel_hi:[0,0,0]
	v_mfma_scale_f32_16x16x128_f8f6f4 v[32:35], v[24:31], v[220:227], v[32:35], v195, v195 op_sel_hi:[0,0,0]
	s_setprio 0
	s_barrier
	s_add_i32 s62, s62, 2
	s_add_u32 s26, s26, 0x100
	s_addc_u32 s27, s27, 0
	s_cmp_gt_u32 s62, 13
	s_cbranch_scc0 .LBB0_818
	s_add_u32 s26, s23, 0xffffff00
	s_addc_u32 s27, s59, -1
	s_andn2_b64 vcc, exec, s[4:5]
	s_cbranch_vccnz .LBB0_809
	v_mov_b32_e32 v32, 0
	s_mov_b32 s6, s16
	s_mov_b32 s10, s18
	s_mov_b64 s[12:13], s[24:25]
	s_mov_b32 s48, s22
	v_mov_b32_e32 v33, v32
	v_mov_b32_e32 v34, v32
	v_mov_b32_e32 v35, v32
	v_mov_b32_e32 v36, v32
	v_mov_b32_e32 v37, v32
	v_mov_b32_e32 v38, v32
	v_mov_b32_e32 v39, v32
	v_mov_b32_e32 v40, v32
	v_mov_b32_e32 v41, v32
	v_mov_b32_e32 v42, v32
	v_mov_b32_e32 v43, v32
	v_mov_b32_e32 v44, v32
	v_mov_b32_e32 v45, v32
	v_mov_b32_e32 v46, v32
	v_mov_b32_e32 v47, v32
	v_mov_b32_e32 v48, v32
	v_mov_b32_e32 v49, v32
	v_mov_b32_e32 v50, v32
	v_mov_b32_e32 v51, v32
	v_mov_b32_e32 v52, v32
	v_mov_b32_e32 v53, v32
	v_mov_b32_e32 v54, v32
	v_mov_b32_e32 v55, v32
	v_mov_b32_e32 v56, v32
	v_mov_b32_e32 v57, v32
	v_mov_b32_e32 v58, v32
	v_mov_b32_e32 v59, v32
	v_mov_b32_e32 v60, v32
	v_mov_b32_e32 v61, v32
	v_mov_b32_e32 v62, v32
	v_mov_b32_e32 v63, v32
	v_mov_b32_e32 v96, v32
	v_mov_b32_e32 v97, v32
	v_mov_b32_e32 v98, v32
	v_mov_b32_e32 v99, v32
	v_mov_b32_e32 v100, v32
	v_mov_b32_e32 v101, v32
	v_mov_b32_e32 v102, v32
	v_mov_b32_e32 v103, v32
	v_mov_b32_e32 v104, v32
	v_mov_b32_e32 v105, v32
	v_mov_b32_e32 v106, v32
	v_mov_b32_e32 v107, v32
	v_mov_b32_e32 v108, v32
	v_mov_b32_e32 v109, v32
	v_mov_b32_e32 v110, v32
	v_mov_b32_e32 v111, v32
	v_mov_b32_e32 v112, v32
	v_mov_b32_e32 v113, v32
	v_mov_b32_e32 v114, v32
	v_mov_b32_e32 v115, v32
	v_mov_b32_e32 v116, v32
	v_mov_b32_e32 v117, v32
	v_mov_b32_e32 v118, v32
	v_mov_b32_e32 v119, v32
	v_mov_b32_e32 v120, v32
	v_mov_b32_e32 v121, v32
	v_mov_b32_e32 v122, v32
	v_mov_b32_e32 v123, v32
	v_mov_b32_e32 v124, v32
	v_mov_b32_e32 v125, v32
	v_mov_b32_e32 v126, v32
	v_mov_b32_e32 v127, v32
	v_mov_b32_e32 v64, v32
	v_mov_b32_e32 v65, v32
	v_mov_b32_e32 v66, v32
	v_mov_b32_e32 v67, v32
	v_mov_b32_e32 v68, v32
	v_mov_b32_e32 v69, v32
	v_mov_b32_e32 v70, v32
	v_mov_b32_e32 v71, v32
	v_mov_b32_e32 v72, v32
	v_mov_b32_e32 v73, v32
	v_mov_b32_e32 v74, v32
	v_mov_b32_e32 v75, v32
	v_mov_b32_e32 v76, v32
	v_mov_b32_e32 v77, v32
	v_mov_b32_e32 v78, v32
	v_mov_b32_e32 v79, v32
	v_mov_b32_e32 v80, v32
	v_mov_b32_e32 v81, v32
	v_mov_b32_e32 v82, v32
	v_mov_b32_e32 v83, v32
	v_mov_b32_e32 v84, v32
	v_mov_b32_e32 v85, v32
	v_mov_b32_e32 v86, v32
	v_mov_b32_e32 v87, v32
	v_mov_b32_e32 v88, v32
	v_mov_b32_e32 v89, v32
	v_mov_b32_e32 v90, v32
	v_mov_b32_e32 v91, v32
	v_mov_b32_e32 v92, v32
	v_mov_b32_e32 v93, v32
	v_mov_b32_e32 v94, v32
	v_mov_b32_e32 v95, v32
	v_mov_b32_e32 v128, v32
	v_mov_b32_e32 v129, v32
	v_mov_b32_e32 v130, v32
	v_mov_b32_e32 v131, v32
	v_mov_b32_e32 v132, v32
	v_mov_b32_e32 v133, v32
	v_mov_b32_e32 v134, v32
	v_mov_b32_e32 v135, v32
	v_mov_b32_e32 v136, v32
	v_mov_b32_e32 v137, v32
	v_mov_b32_e32 v138, v32
	v_mov_b32_e32 v139, v32
	v_mov_b32_e32 v140, v32
	v_mov_b32_e32 v141, v32
	v_mov_b32_e32 v142, v32
	v_mov_b32_e32 v143, v32
	v_mov_b32_e32 v144, v32
	v_mov_b32_e32 v145, v32
	v_mov_b32_e32 v146, v32
	v_mov_b32_e32 v147, v32
	v_mov_b32_e32 v148, v32
	v_mov_b32_e32 v149, v32
	v_mov_b32_e32 v150, v32
	v_mov_b32_e32 v151, v32
	v_mov_b32_e32 v152, v32
	v_mov_b32_e32 v153, v32
	v_mov_b32_e32 v154, v32
	v_mov_b32_e32 v155, v32
	v_mov_b32_e32 v156, v32
	v_mov_b32_e32 v157, v32
	v_mov_b32_e32 v158, v32
	v_mov_b32_e32 v159, v32
	s_andn2_b64 vcc, exec, s[0:1]
	s_cbranch_vccnz .LBB0_810
